# nt hint on the read-once f32 weight loads of the per-layer weight conversion
# speedup vs baseline: 1.0086x; 1.0034x over previous
; #define LAS __attribute__((address_space(3)))
; __device__ __forceinline__ void tr_item(const float* W, int ldw, int c0, bf16* WT, int ldk, int r0, int nblk, int item, LAS float* scr, int lane) {
;     const int kb = item / nblk, nb = item % nblk, k0 = 64 * kb, n0 = 32 * nb;
; #pragma unroll 8
;     for (int i = 0; i < 32; ++i) { const int kk = 2 * i + (lane >> 5); scr[kk * 33 + (lane & 31)] = W[(size_t)(k0 + kk) * ldw + c0 + n0 + (lane & 31)]; }
.LBB0_37:
	s_lshl_b32 s34, s20, 1
	s_lshl_b32 s35, s21, 1
	v_or_b32_e32 v0, s35, v38
	s_add_i32 s36, s34, 4
	s_add_i32 s37, s35, 4
	v_mov_b32_e32 v47, v1
	s_add_i32 s39, s35, 8
	v_lshlrev_b64 v[60:61], 12, v[0:1]
	v_or_b32_e32 v46, s36, v7
	v_or_b32_e32 v0, s37, v38
	v_mov_b32_e32 v45, v1
	v_or_b32_e32 v44, s34, v7
	s_add_i32 s41, s35, 12
	v_lshlrev_b64 v[46:47], 12, v[46:47]
	v_lshlrev_b64 v[62:63], 12, v[0:1]
	v_or_b32_e32 v0, s39, v38
	s_add_i32 s38, s34, 8
	s_add_i32 s40, s34, 12
	s_add_i32 s43, s35, 16
	v_lshlrev_b64 v[44:45], 12, v[44:45]
	v_lshl_add_u64 v[60:61], v[36:37], 0, v[60:61]
	v_lshl_add_u64 v[46:47], v[36:37], 0, v[46:47]
	v_lshlrev_b64 v[64:65], 12, v[0:1]
	v_or_b32_e32 v0, s41, v38
	v_mov_b32_e32 v49, v1
	v_mov_b32_e32 v51, v1
	s_add_i32 s45, s35, 20
	v_or_b32_e32 v48, s38, v7
	v_or_b32_e32 v50, s40, v7
	v_lshl_add_u64 v[44:45], v[36:37], 0, v[44:45]
	v_lshl_add_u64 v[62:63], v[36:37], 0, v[62:63]
	global_load_dword v35, v[60:61], off nt
	global_load_dword v76, v[44:45], off nt
	global_load_dword v77, v[62:63], off nt
	global_load_dword v78, v[46:47], off nt
	v_lshlrev_b64 v[46:47], 12, v[0:1]
	v_or_b32_e32 v0, s43, v38
	s_add_i32 s42, s34, 16
	s_add_i32 s44, s34, 20
	s_add_i32 s47, s35, 24
	v_lshlrev_b64 v[48:49], 12, v[48:49]
	v_lshlrev_b64 v[50:51], 12, v[50:51]
	v_lshl_add_u64 v[44:45], v[36:37], 0, v[64:65]
	v_lshl_add_u64 v[46:47], v[36:37], 0, v[46:47]
	v_lshlrev_b64 v[60:61], 12, v[0:1]
	v_or_b32_e32 v0, s45, v38
	v_mov_b32_e32 v53, v1
	v_mov_b32_e32 v55, v1
	s_add_i32 s46, s34, 24
	s_add_i32 s48, s34, 28
	s_add_i32 s49, s35, 28
	v_or_b32_e32 v52, s42, v7
	v_or_b32_e32 v54, s44, v7
	v_lshl_add_u64 v[48:49], v[36:37], 0, v[48:49]
	v_lshl_add_u64 v[50:51], v[36:37], 0, v[50:51]
	global_load_dword v79, v[44:45], off nt
	global_load_dword v80, v[48:49], off nt
	global_load_dword v81, v[46:47], off nt
	global_load_dword v82, v[50:51], off nt
	v_lshlrev_b64 v[46:47], 12, v[0:1]
	v_or_b32_e32 v0, s47, v38
	v_mov_b32_e32 v57, v1
	v_mov_b32_e32 v59, v1
	v_or_b32_e32 v56, s46, v7
	v_or_b32_e32 v58, s48, v7
	v_lshlrev_b64 v[52:53], 12, v[52:53]
	v_lshlrev_b64 v[54:55], 12, v[54:55]
	v_lshl_add_u64 v[44:45], v[36:37], 0, v[60:61]
	v_lshl_add_u64 v[46:47], v[36:37], 0, v[46:47]
	v_lshlrev_b64 v[48:49], 12, v[0:1]
	v_or_b32_e32 v0, s49, v38
	v_lshlrev_b64 v[56:57], 12, v[56:57]
	v_lshlrev_b64 v[58:59], 12, v[58:59]
	v_lshl_add_u64 v[52:53], v[36:37], 0, v[52:53]
	v_lshl_add_u64 v[54:55], v[36:37], 0, v[54:55]
	global_load_dword v83, v[44:45], off nt
	global_load_dword v84, v[52:53], off nt
	global_load_dword v85, v[46:47], off nt
	global_load_dword v86, v[54:55], off nt
	v_lshl_add_u64 v[44:45], v[36:37], 0, v[48:49]
	v_lshlrev_b64 v[46:47], 12, v[0:1]
	v_lshl_add_u64 v[56:57], v[36:37], 0, v[56:57]
	v_lshl_add_u64 v[58:59], v[36:37], 0, v[58:59]
	v_lshl_add_u64 v[46:47], v[36:37], 0, v[46:47]
	global_load_dword v0, v[44:45], off nt
	global_load_dword v87, v[56:57], off nt
	global_load_dword v88, v[46:47], off nt
	global_load_dword v89, v[58:59], off nt
	v_or_b32_e32 v46, s34, v3
	v_or_b32_e32 v44, s35, v2
	s_add_i32 s21, s21, 16
	s_add_i32 s20, s20, 16
	s_add_i32 s31, s31, -16
	v_mad_u64_u32 v[44:45], s[10:11], v44, s27, v[6:7]
	v_mad_u64_u32 v[46:47], s[10:11], v46, s27, v[6:7]
	v_or_b32_e32 v45, s36, v3
	v_or_b32_e32 v47, s37, v2
	v_or_b32_e32 v54, s38, v3
	v_or_b32_e32 v52, s39, v2
	v_or_b32_e32 v58, s40, v3
	v_or_b32_e32 v56, s41, v2
	v_or_b32_e32 v62, s42, v3
	v_or_b32_e32 v60, s43, v2
	v_or_b32_e32 v66, s44, v3
	v_or_b32_e32 v64, s45, v2
	v_or_b32_e32 v70, s46, v3
	v_or_b32_e32 v68, s47, v2
	v_or_b32_e32 v74, s48, v3
	v_or_b32_e32 v72, s49, v2
	s_cmp_lg_u32 s31, 0
	v_mad_u64_u32 v[48:49], s[10:11], v47, s27, v[6:7]
	v_mad_u64_u32 v[50:51], s[10:11], v45, s27, v[6:7]
	v_mad_u64_u32 v[52:53], s[10:11], v52, s27, v[6:7]
	v_mad_u64_u32 v[54:55], s[10:11], v54, s27, v[6:7]
	v_mad_u64_u32 v[56:57], s[10:11], v56, s27, v[6:7]
	v_mad_u64_u32 v[58:59], s[10:11], v58, s27, v[6:7]
	v_mad_u64_u32 v[60:61], s[10:11], v60, s27, v[6:7]
	v_mad_u64_u32 v[62:63], s[10:11], v62, s27, v[6:7]
	v_mad_u64_u32 v[64:65], s[10:11], v64, s27, v[6:7]
	v_mad_u64_u32 v[66:67], s[10:11], v66, s27, v[6:7]
	v_mad_u64_u32 v[68:69], s[10:11], v68, s27, v[6:7]
	v_mad_u64_u32 v[70:71], s[10:11], v70, s27, v[6:7]
	v_mad_u64_u32 v[72:73], s[10:11], v72, s27, v[6:7]
	v_mad_u64_u32 v[74:75], s[10:11], v74, s27, v[6:7]
	s_waitcnt vmcnt(15)
	ds_write_b32 v44, v35
	s_waitcnt vmcnt(14)
	ds_write_b32 v46, v76
	s_waitcnt vmcnt(13)
	ds_write_b32 v48, v77
	s_waitcnt vmcnt(12)
	ds_write_b32 v50, v78
	s_waitcnt vmcnt(11)
	ds_write_b32 v52, v79
	s_waitcnt vmcnt(10)
	ds_write_b32 v54, v80
	s_waitcnt vmcnt(9)
	ds_write_b32 v56, v81
	s_waitcnt vmcnt(8)
	ds_write_b32 v58, v82
	s_waitcnt vmcnt(7)
	ds_write_b32 v60, v83
	s_waitcnt vmcnt(6)
	ds_write_b32 v62, v84
	s_waitcnt vmcnt(5)
	ds_write_b32 v64, v85
	s_waitcnt vmcnt(4)
	ds_write_b32 v66, v86
	s_waitcnt vmcnt(3)
	ds_write_b32 v68, v0
	s_waitcnt vmcnt(2)
	ds_write_b32 v70, v87
	s_waitcnt vmcnt(1)
	ds_write_b32 v72, v88
	s_waitcnt vmcnt(0)
	ds_write_b32 v74, v89
	s_cbranch_scc1 .LBB0_37
; #define LAS __attribute__((address_space(3)))
; __device__ __forceinline__ unsigned pk2(float lo, float hi) { return f2bf(lo) | (f2bf(hi) << 16); }
; __device__ __forceinline__ void tr_item(const float* W, int ldw, int c0, bf16* WT, int ldk, int r0, int nblk, int item, LAS float* scr, int lane) {
;     ...
;     asm volatile("s_waitcnt lgkmcnt(0)" ::: "memory");
;     const int c = lane & 7;
; #pragma unroll
;     for (int j = 0; j < 4; ++j) { const int n = (lane >> 3) + 8 * j; const LAS float* s = scr + (8 * c) * 33 + n;
;         v4u o; o.x = pk2(s[0 * 33], s[1 * 33]); o.y = pk2(s[2 * 33], s[3 * 33]); o.z = pk2(s[4 * 33], s[5 * 33]); o.w = pk2(s[6 * 33], s[7 * 33]);
;         *(v4u*)(WT + (size_t)(r0 + n0 + n) * ldk + k0 + 8 * c) = o; }
;     asm volatile("s_waitcnt lgkmcnt(0)" ::: "memory");
	s_waitcnt lgkmcnt(0)
	ds_read2_b32 v[36:37], v40 offset1:8
	ds_read2_b32 v[50:51], v40 offset0:33 offset1:41
	ds_read2_b32 v[52:53], v40 offset0:66 offset1:74
	ds_read2_b32 v[54:55], v40 offset0:99 offset1:107
	ds_read2_b32 v[56:57], v40 offset0:132 offset1:140
	s_mov_b32 s85, 0xffff0000
	s_waitcnt lgkmcnt(4)
	v_bfe_u32 v0, v36, 16, 1
	v_add3_u32 v0, v36, v0, s80
	s_waitcnt lgkmcnt(3)
	v_bfe_u32 v7, v50, 16, 1
	v_lshrrev_b32_e32 v0, 16, v0
	v_add3_u32 v7, v50, v7, s80
	ds_read2_b32 v[58:59], v40 offset0:165 offset1:173
	v_and_or_b32 v44, v7, s85, v0
	s_waitcnt lgkmcnt(3)
	v_bfe_u32 v0, v52, 16, 1
	v_add3_u32 v0, v52, v0, s80
	s_waitcnt lgkmcnt(2)
	v_bfe_u32 v7, v54, 16, 1
	ds_read2_b32 v[60:61], v40 offset0:198 offset1:206
	v_lshrrev_b32_e32 v0, 16, v0
	v_add3_u32 v7, v54, v7, s80
	ds_read2_b32 v[62:63], v40 offset0:231 offset1:239
	v_and_or_b32 v45, v7, s85, v0
	s_waitcnt lgkmcnt(3)
	v_bfe_u32 v0, v56, 16, 1
	v_add3_u32 v0, v56, v0, s80
	s_waitcnt lgkmcnt(2)
	v_bfe_u32 v7, v58, 16, 1
	v_lshrrev_b32_e32 v0, 16, v0
	v_add3_u32 v7, v58, v7, s80
	v_and_or_b32 v46, v7, s85, v0
	s_waitcnt lgkmcnt(1)
	v_bfe_u32 v0, v60, 16, 1
	v_add3_u32 v0, v60, v0, s80
	s_waitcnt lgkmcnt(0)
	v_bfe_u32 v7, v62, 16, 1
	v_lshrrev_b32_e32 v0, 16, v0
	v_add3_u32 v7, v62, v7, s80
	s_lshl_b32 s88, s4, 1
	v_and_or_b32 v47, v7, s85, v0
	v_or_b32_e32 v0, s1, v39
	v_lshl_add_u64 v[48:49], v[10:11], 0, s[88:89]
	v_lshlrev_b32_e32 v0, 13, v0
	v_lshl_add_u64 v[64:65], v[48:49], 0, v[0:1]
	v_bfe_u32 v0, v37, 16, 1
	v_add3_u32 v0, v37, v0, s80
	v_bfe_u32 v7, v51, 16, 1
	v_lshrrev_b32_e32 v0, 16, v0
	v_add3_u32 v7, v51, v7, s80
	global_store_dwordx4 v[64:65], v[44:47], off
	ds_read2_b32 v[36:37], v40 offset0:16 offset1:24
	s_mov_b64 s[20:21], 0
	v_and_or_b32 v44, v7, s85, v0
	v_bfe_u32 v0, v53, 16, 1
	v_add3_u32 v0, v53, v0, s80
	v_bfe_u32 v7, v55, 16, 1
	v_lshrrev_b32_e32 v0, 16, v0
	v_add3_u32 v7, v55, v7, s80
	v_and_or_b32 v45, v7, s85, v0
	v_bfe_u32 v0, v57, 16, 1
	v_add3_u32 v0, v57, v0, s80
	v_bfe_u32 v7, v59, 16, 1
	v_lshrrev_b32_e32 v0, 16, v0
	v_add3_u32 v7, v59, v7, s80
	v_and_or_b32 v46, v7, s85, v0
	v_bfe_u32 v0, v61, 16, 1
	v_add3_u32 v0, v61, v0, s80
	v_bfe_u32 v7, v63, 16, 1
	v_lshrrev_b32_e32 v0, 16, v0
	v_add3_u32 v7, v63, v7, s80
	v_and_or_b32 v47, v7, s85, v0
	v_or_b32_e32 v0, s1, v41
	v_lshlrev_b32_e32 v0, 13, v0
	v_lshl_add_u64 v[50:51], v[48:49], 0, v[0:1]
	global_store_dwordx4 v[50:51], v[44:47], off
	ds_read2_b32 v[50:51], v40 offset0:49 offset1:57
	ds_read2_b32 v[52:53], v40 offset0:82 offset1:90
	ds_read2_b32 v[54:55], v40 offset0:115 offset1:123
	s_waitcnt lgkmcnt(3)
	v_bfe_u32 v0, v36, 16, 1
	v_add3_u32 v0, v36, v0, s80
	s_waitcnt lgkmcnt(2)
	v_bfe_u32 v7, v50, 16, 1
	ds_read2_b32 v[56:57], v40 offset0:148 offset1:156
	v_lshrrev_b32_e32 v0, 16, v0
	v_add3_u32 v7, v50, v7, s80
	ds_read2_b32 v[58:59], v40 offset0:181 offset1:189
	v_and_or_b32 v44, v7, s85, v0
	s_waitcnt lgkmcnt(3)
	v_bfe_u32 v0, v52, 16, 1
	v_add3_u32 v0, v52, v0, s80
	s_waitcnt lgkmcnt(2)
	v_bfe_u32 v7, v54, 16, 1
	ds_read2_b32 v[60:61], v40 offset0:214 offset1:222
	v_lshrrev_b32_e32 v0, 16, v0
	v_add3_u32 v7, v54, v7, s80
	ds_read2_b32 v[62:63], v40 offset0:247 offset1:255
	v_and_or_b32 v45, v7, s85, v0
	s_waitcnt lgkmcnt(3)
	v_bfe_u32 v0, v56, 16, 1
	v_add3_u32 v0, v56, v0, s80
	s_waitcnt lgkmcnt(2)
	v_bfe_u32 v7, v58, 16, 1
	v_lshrrev_b32_e32 v0, 16, v0
	v_add3_u32 v7, v58, v7, s80
	v_and_or_b32 v46, v7, s85, v0
	s_waitcnt lgkmcnt(1)
	v_bfe_u32 v0, v60, 16, 1
	v_add3_u32 v0, v60, v0, s80
	s_waitcnt lgkmcnt(0)
	v_bfe_u32 v7, v62, 16, 1
	v_lshrrev_b32_e32 v0, 16, v0
	v_add3_u32 v7, v62, v7, s80
	v_and_or_b32 v47, v7, s85, v0
	v_or_b32_e32 v0, s1, v42
	v_lshlrev_b32_e32 v0, 13, v0
	v_lshl_add_u64 v[64:65], v[48:49], 0, v[0:1]
	v_bfe_u32 v0, v37, 16, 1
	v_add3_u32 v0, v37, v0, s80
	v_bfe_u32 v7, v51, 16, 1
	v_lshrrev_b32_e32 v0, 16, v0
	v_add3_u32 v7, v51, v7, s80
	global_store_dwordx4 v[64:65], v[44:47], off
	v_readlane_b32 s81, v254, 55
	s_nop 0
	v_and_or_b32 v44, v7, s85, v0
	v_bfe_u32 v0, v53, 16, 1
	v_add3_u32 v0, v53, v0, s80
	v_bfe_u32 v7, v55, 16, 1
	v_lshrrev_b32_e32 v0, 16, v0
	v_add3_u32 v7, v55, v7, s80
	v_and_or_b32 v45, v7, s85, v0
	v_bfe_u32 v0, v57, 16, 1
	v_add3_u32 v0, v57, v0, s80
	v_bfe_u32 v7, v59, 16, 1
	v_lshrrev_b32_e32 v0, 16, v0
	v_add3_u32 v7, v59, v7, s80
	v_and_or_b32 v46, v7, s85, v0
	v_bfe_u32 v0, v61, 16, 1
	v_add3_u32 v0, v61, v0, s80
	v_bfe_u32 v7, v63, 16, 1
	v_lshrrev_b32_e32 v0, 16, v0
	v_add3_u32 v7, v63, v7, s80
	v_and_or_b32 v47, v7, s85, v0
	v_or_b32_e32 v0, s1, v43
	v_lshlrev_b32_e32 v0, 13, v0
	v_lshl_add_u64 v[36:37], v[48:49], 0, v[0:1]
	global_store_dwordx4 v[36:37], v[44:47], off
	s_waitcnt lgkmcnt(0)

; #define LAS __attribute__((address_space(3)))
; __device__ __forceinline__ void tr_item(const float* W, int ldw, int c0, bf16* WT, int ldk, int r0, int nblk, int item, LAS float* scr, int lane) {
;     const int kb = item / nblk, nb = item % nblk, k0 = 64 * kb, n0 = 32 * nb;
; #pragma unroll 8
;     for (int i = 0; i < 32; ++i) { const int kk = 2 * i + (lane >> 5); scr[kk * 33 + (lane & 31)] = W[(size_t)(k0 + kk) * ldw + c0 + n0 + (lane & 31)]; }
.LBB0_41:
	s_lshl_b32 s34, s20, 1
	s_lshl_b32 s35, s21, 1
	v_or_b32_e32 v0, s35, v38
	s_add_i32 s36, s34, 4
	s_add_i32 s37, s35, 4
	v_mov_b32_e32 v47, v1
	s_add_i32 s39, s35, 8
	v_lshlrev_b64 v[60:61], 14, v[0:1]
	v_or_b32_e32 v46, s36, v7
	v_or_b32_e32 v0, s37, v38
	v_mov_b32_e32 v45, v1
	v_or_b32_e32 v44, s34, v7
	s_add_i32 s41, s35, 12
	v_lshlrev_b64 v[46:47], 14, v[46:47]
	v_lshlrev_b64 v[62:63], 14, v[0:1]
	v_or_b32_e32 v0, s39, v38
	s_add_i32 s38, s34, 8
	s_add_i32 s40, s34, 12
	s_add_i32 s43, s35, 16
	v_lshlrev_b64 v[44:45], 14, v[44:45]
	v_lshl_add_u64 v[60:61], v[36:37], 0, v[60:61]
	v_lshl_add_u64 v[46:47], v[36:37], 0, v[46:47]
	v_lshlrev_b64 v[64:65], 14, v[0:1]
	v_or_b32_e32 v0, s41, v38
	v_mov_b32_e32 v49, v1
	v_mov_b32_e32 v51, v1
	s_add_i32 s45, s35, 20
	v_or_b32_e32 v48, s38, v7
	v_or_b32_e32 v50, s40, v7
	v_lshl_add_u64 v[44:45], v[36:37], 0, v[44:45]
	v_lshl_add_u64 v[62:63], v[36:37], 0, v[62:63]
	global_load_dword v35, v[60:61], off nt
	global_load_dword v76, v[44:45], off nt
	global_load_dword v77, v[62:63], off nt
	global_load_dword v78, v[46:47], off nt
	v_lshlrev_b64 v[46:47], 14, v[0:1]
	v_or_b32_e32 v0, s43, v38
	s_add_i32 s42, s34, 16
	s_add_i32 s44, s34, 20
	s_add_i32 s47, s35, 24
	v_lshlrev_b64 v[48:49], 14, v[48:49]
	v_lshlrev_b64 v[50:51], 14, v[50:51]
	v_lshl_add_u64 v[44:45], v[36:37], 0, v[64:65]
	v_lshl_add_u64 v[46:47], v[36:37], 0, v[46:47]
	v_lshlrev_b64 v[60:61], 14, v[0:1]
	v_or_b32_e32 v0, s45, v38
	v_mov_b32_e32 v53, v1
	v_mov_b32_e32 v55, v1
	s_add_i32 s46, s34, 24
	s_add_i32 s48, s34, 28
	s_add_i32 s49, s35, 28
	v_or_b32_e32 v52, s42, v7
	v_or_b32_e32 v54, s44, v7
	v_lshl_add_u64 v[48:49], v[36:37], 0, v[48:49]
	v_lshl_add_u64 v[50:51], v[36:37], 0, v[50:51]
	global_load_dword v79, v[44:45], off nt
	global_load_dword v80, v[48:49], off nt
	global_load_dword v81, v[46:47], off nt
	global_load_dword v82, v[50:51], off nt
	v_lshlrev_b64 v[46:47], 14, v[0:1]
	v_or_b32_e32 v0, s47, v38
	v_mov_b32_e32 v57, v1
	v_mov_b32_e32 v59, v1
	v_or_b32_e32 v56, s46, v7
	v_or_b32_e32 v58, s48, v7
	v_lshlrev_b64 v[52:53], 14, v[52:53]
	v_lshlrev_b64 v[54:55], 14, v[54:55]
	v_lshl_add_u64 v[44:45], v[36:37], 0, v[60:61]
	v_lshl_add_u64 v[46:47], v[36:37], 0, v[46:47]
	v_lshlrev_b64 v[48:49], 14, v[0:1]
	v_or_b32_e32 v0, s49, v38
	v_lshlrev_b64 v[56:57], 14, v[56:57]
	v_lshlrev_b64 v[58:59], 14, v[58:59]
	v_lshl_add_u64 v[52:53], v[36:37], 0, v[52:53]
	v_lshl_add_u64 v[54:55], v[36:37], 0, v[54:55]
	global_load_dword v83, v[44:45], off nt
	global_load_dword v84, v[52:53], off nt
	global_load_dword v85, v[46:47], off nt
	global_load_dword v86, v[54:55], off nt
	v_lshl_add_u64 v[44:45], v[36:37], 0, v[48:49]
	v_lshlrev_b64 v[46:47], 14, v[0:1]
	v_lshl_add_u64 v[56:57], v[36:37], 0, v[56:57]
	v_lshl_add_u64 v[58:59], v[36:37], 0, v[58:59]
	v_lshl_add_u64 v[46:47], v[36:37], 0, v[46:47]
	global_load_dword v0, v[44:45], off nt
	global_load_dword v87, v[56:57], off nt
	global_load_dword v88, v[46:47], off nt
	global_load_dword v89, v[58:59], off nt
	v_or_b32_e32 v46, s34, v3
	v_or_b32_e32 v44, s35, v2
	s_add_i32 s21, s21, 16
	s_add_i32 s20, s20, 16
	s_add_i32 s31, s31, -16
	v_mad_u64_u32 v[44:45], s[10:11], v44, s27, v[6:7]
	v_mad_u64_u32 v[46:47], s[10:11], v46, s27, v[6:7]
	v_or_b32_e32 v45, s36, v3
	v_or_b32_e32 v47, s37, v2
	v_or_b32_e32 v54, s38, v3
	v_or_b32_e32 v52, s39, v2
	v_or_b32_e32 v58, s40, v3
	v_or_b32_e32 v56, s41, v2
	v_or_b32_e32 v62, s42, v3
	v_or_b32_e32 v60, s43, v2
	v_or_b32_e32 v66, s44, v3
	v_or_b32_e32 v64, s45, v2
	v_or_b32_e32 v70, s46, v3
	v_or_b32_e32 v68, s47, v2
	v_or_b32_e32 v74, s48, v3
	v_or_b32_e32 v72, s49, v2
	s_cmp_lg_u32 s31, 0
	v_mad_u64_u32 v[48:49], s[10:11], v47, s27, v[6:7]
	v_mad_u64_u32 v[50:51], s[10:11], v45, s27, v[6:7]
	v_mad_u64_u32 v[52:53], s[10:11], v52, s27, v[6:7]
	v_mad_u64_u32 v[54:55], s[10:11], v54, s27, v[6:7]
	v_mad_u64_u32 v[56:57], s[10:11], v56, s27, v[6:7]
	v_mad_u64_u32 v[58:59], s[10:11], v58, s27, v[6:7]
	v_mad_u64_u32 v[60:61], s[10:11], v60, s27, v[6:7]
	v_mad_u64_u32 v[62:63], s[10:11], v62, s27, v[6:7]
	v_mad_u64_u32 v[64:65], s[10:11], v64, s27, v[6:7]
	v_mad_u64_u32 v[66:67], s[10:11], v66, s27, v[6:7]
	v_mad_u64_u32 v[68:69], s[10:11], v68, s27, v[6:7]
	v_mad_u64_u32 v[70:71], s[10:11], v70, s27, v[6:7]
	v_mad_u64_u32 v[72:73], s[10:11], v72, s27, v[6:7]
	v_mad_u64_u32 v[74:75], s[10:11], v74, s27, v[6:7]
	s_waitcnt vmcnt(15)
	ds_write_b32 v44, v35
	s_waitcnt vmcnt(14)
	ds_write_b32 v46, v76
	s_waitcnt vmcnt(13)
	ds_write_b32 v48, v77
	s_waitcnt vmcnt(12)
	ds_write_b32 v50, v78
	s_waitcnt vmcnt(11)
	ds_write_b32 v52, v79
	s_waitcnt vmcnt(10)
	ds_write_b32 v54, v80
	s_waitcnt vmcnt(9)
	ds_write_b32 v56, v81
	s_waitcnt vmcnt(8)
	ds_write_b32 v58, v82
	s_waitcnt vmcnt(7)
	ds_write_b32 v60, v83
	s_waitcnt vmcnt(6)
	ds_write_b32 v62, v84
	s_waitcnt vmcnt(5)
	ds_write_b32 v64, v85
	s_waitcnt vmcnt(4)
	ds_write_b32 v66, v86
	s_waitcnt vmcnt(3)
	ds_write_b32 v68, v0
	s_waitcnt vmcnt(2)
	ds_write_b32 v70, v87
	s_waitcnt vmcnt(1)
	ds_write_b32 v72, v88
	s_waitcnt vmcnt(0)
	ds_write_b32 v74, v89
	s_cbranch_scc1 .LBB0_41
; #define LAS __attribute__((address_space(3)))
; __device__ __forceinline__ unsigned pk2(float lo, float hi) { return f2bf(lo) | (f2bf(hi) << 16); }
; __device__ __forceinline__ void tr_item(const float* W, int ldw, int c0, bf16* WT, int ldk, int r0, int nblk, int item, LAS float* scr, int lane) {
;     ...
;     asm volatile("s_waitcnt lgkmcnt(0)" ::: "memory");
;     const int c = lane & 7;
; #pragma unroll
;     for (int j = 0; j < 4; ++j) { const int n = (lane >> 3) + 8 * j; const LAS float* s = scr + (8 * c) * 33 + n;
;         v4u o; o.x = pk2(s[0 * 33], s[1 * 33]); o.y = pk2(s[2 * 33], s[3 * 33]); o.z = pk2(s[4 * 33], s[5 * 33]); o.w = pk2(s[6 * 33], s[7 * 33]);
;         *(v4u*)(WT + (size_t)(r0 + n0 + n) * ldk + k0 + 8 * c) = o; }
;     asm volatile("s_waitcnt lgkmcnt(0)" ::: "memory");
	s_waitcnt lgkmcnt(0)
	ds_read2_b32 v[36:37], v40 offset1:8
	ds_read2_b32 v[50:51], v40 offset0:33 offset1:41
	ds_read2_b32 v[52:53], v40 offset0:66 offset1:74
	ds_read2_b32 v[54:55], v40 offset0:99 offset1:107
	ds_read2_b32 v[56:57], v40 offset0:132 offset1:140
	s_mov_b32 s85, 0xffff0000
	s_waitcnt lgkmcnt(4)
	v_bfe_u32 v0, v36, 16, 1
	v_add3_u32 v0, v36, v0, s80
	s_waitcnt lgkmcnt(3)
	v_bfe_u32 v7, v50, 16, 1
	v_lshrrev_b32_e32 v0, 16, v0
	v_add3_u32 v7, v50, v7, s80
	ds_read2_b32 v[58:59], v40 offset0:165 offset1:173
	v_and_or_b32 v44, v7, s85, v0
	s_waitcnt lgkmcnt(3)
	v_bfe_u32 v0, v52, 16, 1
	v_add3_u32 v0, v52, v0, s80
	s_waitcnt lgkmcnt(2)
	v_bfe_u32 v7, v54, 16, 1
	ds_read2_b32 v[60:61], v40 offset0:198 offset1:206
	v_lshrrev_b32_e32 v0, 16, v0
	v_add3_u32 v7, v54, v7, s80
	ds_read2_b32 v[62:63], v40 offset0:231 offset1:239
	v_and_or_b32 v45, v7, s85, v0
	s_waitcnt lgkmcnt(3)
	v_bfe_u32 v0, v56, 16, 1
	v_add3_u32 v0, v56, v0, s80
	s_waitcnt lgkmcnt(2)
	v_bfe_u32 v7, v58, 16, 1
	v_lshrrev_b32_e32 v0, 16, v0
	v_add3_u32 v7, v58, v7, s80
	v_and_or_b32 v46, v7, s85, v0
	s_waitcnt lgkmcnt(1)
	v_bfe_u32 v0, v60, 16, 1
	v_add3_u32 v0, v60, v0, s80
	s_waitcnt lgkmcnt(0)
	v_bfe_u32 v7, v62, 16, 1
	v_lshrrev_b32_e32 v0, 16, v0
	v_add3_u32 v7, v62, v7, s80
	s_lshl_b32 s88, s4, 1
	v_and_or_b32 v47, v7, s85, v0
	v_or_b32_e32 v0, s1, v39
	v_lshl_add_u64 v[48:49], v[14:15], 0, s[88:89]
	v_lshlrev_b32_e32 v0, 11, v0
	v_lshl_add_u64 v[64:65], v[48:49], 0, v[0:1]
	v_bfe_u32 v0, v37, 16, 1
	v_add3_u32 v0, v37, v0, s80
	v_bfe_u32 v7, v51, 16, 1
	v_lshrrev_b32_e32 v0, 16, v0
	v_add3_u32 v7, v51, v7, s80
	global_store_dwordx4 v[64:65], v[44:47], off
	ds_read2_b32 v[36:37], v40 offset0:16 offset1:24
	v_readlane_b32 s81, v254, 55
	v_and_or_b32 v44, v7, s85, v0
	v_bfe_u32 v0, v53, 16, 1
	v_add3_u32 v0, v53, v0, s80
	v_bfe_u32 v7, v55, 16, 1
	v_lshrrev_b32_e32 v0, 16, v0
	v_add3_u32 v7, v55, v7, s80
	v_and_or_b32 v45, v7, s85, v0
	v_bfe_u32 v0, v57, 16, 1
	v_add3_u32 v0, v57, v0, s80
	v_bfe_u32 v7, v59, 16, 1
	v_lshrrev_b32_e32 v0, 16, v0
	v_add3_u32 v7, v59, v7, s80
	v_and_or_b32 v46, v7, s85, v0
	v_bfe_u32 v0, v61, 16, 1
	v_add3_u32 v0, v61, v0, s80
	v_bfe_u32 v7, v63, 16, 1
	v_lshrrev_b32_e32 v0, 16, v0
	v_add3_u32 v7, v63, v7, s80
	v_and_or_b32 v47, v7, s85, v0
	v_or_b32_e32 v0, s1, v41
	v_lshlrev_b32_e32 v0, 11, v0
	v_lshl_add_u64 v[50:51], v[48:49], 0, v[0:1]
	global_store_dwordx4 v[50:51], v[44:47], off
	ds_read2_b32 v[50:51], v40 offset0:49 offset1:57
	ds_read2_b32 v[52:53], v40 offset0:82 offset1:90
	ds_read2_b32 v[54:55], v40 offset0:115 offset1:123
	s_waitcnt lgkmcnt(3)
	v_bfe_u32 v0, v36, 16, 1
	v_add3_u32 v0, v36, v0, s80
	s_waitcnt lgkmcnt(2)
	v_bfe_u32 v7, v50, 16, 1
	ds_read2_b32 v[56:57], v40 offset0:148 offset1:156
	v_lshrrev_b32_e32 v0, 16, v0
	v_add3_u32 v7, v50, v7, s80
	ds_read2_b32 v[58:59], v40 offset0:181 offset1:189
	v_and_or_b32 v44, v7, s85, v0
	s_waitcnt lgkmcnt(3)
	v_bfe_u32 v0, v52, 16, 1
	v_add3_u32 v0, v52, v0, s80
	s_waitcnt lgkmcnt(2)
	v_bfe_u32 v7, v54, 16, 1
	ds_read2_b32 v[60:61], v40 offset0:214 offset1:222
	v_lshrrev_b32_e32 v0, 16, v0
	v_add3_u32 v7, v54, v7, s80
	ds_read2_b32 v[62:63], v40 offset0:247 offset1:255
	v_and_or_b32 v45, v7, s85, v0
	s_waitcnt lgkmcnt(3)
	v_bfe_u32 v0, v56, 16, 1
	v_add3_u32 v0, v56, v0, s80
	s_waitcnt lgkmcnt(2)
	v_bfe_u32 v7, v58, 16, 1
	v_lshrrev_b32_e32 v0, 16, v0
	v_add3_u32 v7, v58, v7, s80
	v_and_or_b32 v46, v7, s85, v0
	s_waitcnt lgkmcnt(1)
	v_bfe_u32 v0, v60, 16, 1
	v_add3_u32 v0, v60, v0, s80
	s_waitcnt lgkmcnt(0)
	v_bfe_u32 v7, v62, 16, 1
	v_lshrrev_b32_e32 v0, 16, v0
	v_add3_u32 v7, v62, v7, s80
	v_and_or_b32 v47, v7, s85, v0
	v_or_b32_e32 v0, s1, v42
	v_lshlrev_b32_e32 v0, 11, v0
	v_lshl_add_u64 v[64:65], v[48:49], 0, v[0:1]
	v_bfe_u32 v0, v37, 16, 1
	v_add3_u32 v0, v37, v0, s80
	v_bfe_u32 v7, v51, 16, 1
	v_lshrrev_b32_e32 v0, 16, v0
	v_add3_u32 v7, v51, v7, s80
	global_store_dwordx4 v[64:65], v[44:47], off
	s_nop 1
	v_and_or_b32 v44, v7, s85, v0
	v_bfe_u32 v0, v53, 16, 1
	v_add3_u32 v0, v53, v0, s80
	v_bfe_u32 v7, v55, 16, 1
	v_lshrrev_b32_e32 v0, 16, v0
	v_add3_u32 v7, v55, v7, s80
	v_and_or_b32 v45, v7, s85, v0
	v_bfe_u32 v0, v57, 16, 1
	v_add3_u32 v0, v57, v0, s80
	v_bfe_u32 v7, v59, 16, 1
	v_lshrrev_b32_e32 v0, 16, v0
	v_add3_u32 v7, v59, v7, s80
	v_and_or_b32 v46, v7, s85, v0
	v_bfe_u32 v0, v61, 16, 1
	v_add3_u32 v0, v61, v0, s80
	v_bfe_u32 v7, v63, 16, 1
	v_lshrrev_b32_e32 v0, 16, v0
	v_add3_u32 v7, v63, v7, s80
	v_and_or_b32 v47, v7, s85, v0
	v_or_b32_e32 v0, s1, v43
	v_lshlrev_b32_e32 v0, 11, v0
	v_lshl_add_u64 v[36:37], v[48:49], 0, v[0:1]
	global_store_dwordx4 v[36:37], v[44:47], off
	s_waitcnt lgkmcnt(0)

; #define LAS __attribute__((address_space(3)))
; __device__ __forceinline__ void tr_item(const float* W, int ldw, int c0, bf16* WT, int ldk, int r0, int nblk, int item, LAS float* scr, int lane) {
;     const int kb = item / nblk, nb = item % nblk, k0 = 64 * kb, n0 = 32 * nb;
; #pragma unroll 8
;     for (int i = 0; i < 32; ++i) { const int kk = 2 * i + (lane >> 5); scr[kk * 33 + (lane & 31)] = W[(size_t)(k0 + kk) * ldw + c0 + n0 + (lane & 31)]; }
.LBB0_46:
	s_lshl_b32 s34, s20, 1
	s_lshl_b32 s35, s21, 1
	v_or_b32_e32 v0, s35, v38
	s_add_i32 s36, s34, 4
	s_add_i32 s37, s35, 4
	v_mov_b32_e32 v47, v1
	s_add_i32 s39, s35, 8
	v_lshlrev_b64 v[60:61], 12, v[0:1]
	v_or_b32_e32 v46, s36, v7
	v_or_b32_e32 v0, s37, v38
	v_mov_b32_e32 v45, v1
	v_or_b32_e32 v44, s34, v7
	s_add_i32 s41, s35, 12
	v_lshlrev_b64 v[46:47], 12, v[46:47]
	v_lshlrev_b64 v[62:63], 12, v[0:1]
	v_or_b32_e32 v0, s39, v38
	s_add_i32 s38, s34, 8
	s_add_i32 s40, s34, 12
	s_add_i32 s43, s35, 16
	v_lshlrev_b64 v[44:45], 12, v[44:45]
	v_lshl_add_u64 v[60:61], v[36:37], 0, v[60:61]
	v_lshl_add_u64 v[46:47], v[36:37], 0, v[46:47]
	v_lshlrev_b64 v[64:65], 12, v[0:1]
	v_or_b32_e32 v0, s41, v38
	v_mov_b32_e32 v49, v1
	v_mov_b32_e32 v51, v1
	s_add_i32 s45, s35, 20
	v_or_b32_e32 v48, s38, v7
	v_or_b32_e32 v50, s40, v7
	v_lshl_add_u64 v[44:45], v[36:37], 0, v[44:45]
	v_lshl_add_u64 v[62:63], v[36:37], 0, v[62:63]
	global_load_dword v35, v[60:61], off nt
	global_load_dword v76, v[44:45], off nt
	global_load_dword v77, v[62:63], off nt
	global_load_dword v78, v[46:47], off nt
	v_lshlrev_b64 v[46:47], 12, v[0:1]
	v_or_b32_e32 v0, s43, v38
	s_add_i32 s42, s34, 16
	s_add_i32 s44, s34, 20
	s_add_i32 s47, s35, 24
	v_lshlrev_b64 v[48:49], 12, v[48:49]
	v_lshlrev_b64 v[50:51], 12, v[50:51]
	v_lshl_add_u64 v[44:45], v[36:37], 0, v[64:65]
	v_lshl_add_u64 v[46:47], v[36:37], 0, v[46:47]
	v_lshlrev_b64 v[60:61], 12, v[0:1]
	v_or_b32_e32 v0, s45, v38
	v_mov_b32_e32 v53, v1
	v_mov_b32_e32 v55, v1
	s_add_i32 s46, s34, 24
	s_add_i32 s48, s34, 28
	s_add_i32 s49, s35, 28
	v_or_b32_e32 v52, s42, v7
	v_or_b32_e32 v54, s44, v7
	v_lshl_add_u64 v[48:49], v[36:37], 0, v[48:49]
	v_lshl_add_u64 v[50:51], v[36:37], 0, v[50:51]
	global_load_dword v79, v[44:45], off nt
	global_load_dword v80, v[48:49], off nt
	global_load_dword v81, v[46:47], off nt
	global_load_dword v82, v[50:51], off nt
	v_lshlrev_b64 v[46:47], 12, v[0:1]
	v_or_b32_e32 v0, s47, v38
	v_mov_b32_e32 v57, v1
	v_mov_b32_e32 v59, v1
	v_or_b32_e32 v56, s46, v7
	v_or_b32_e32 v58, s48, v7
	v_lshlrev_b64 v[52:53], 12, v[52:53]
	v_lshlrev_b64 v[54:55], 12, v[54:55]
	v_lshl_add_u64 v[44:45], v[36:37], 0, v[60:61]
	v_lshl_add_u64 v[46:47], v[36:37], 0, v[46:47]
	v_lshlrev_b64 v[48:49], 12, v[0:1]
	v_or_b32_e32 v0, s49, v38
	v_lshlrev_b64 v[56:57], 12, v[56:57]
	v_lshlrev_b64 v[58:59], 12, v[58:59]
	v_lshl_add_u64 v[52:53], v[36:37], 0, v[52:53]
	v_lshl_add_u64 v[54:55], v[36:37], 0, v[54:55]
	global_load_dword v83, v[44:45], off nt
	global_load_dword v84, v[52:53], off nt
	global_load_dword v85, v[46:47], off nt
	global_load_dword v86, v[54:55], off nt
	v_lshl_add_u64 v[44:45], v[36:37], 0, v[48:49]
	v_lshlrev_b64 v[46:47], 12, v[0:1]
	v_lshl_add_u64 v[56:57], v[36:37], 0, v[56:57]
	v_lshl_add_u64 v[58:59], v[36:37], 0, v[58:59]
	v_lshl_add_u64 v[46:47], v[36:37], 0, v[46:47]
	global_load_dword v0, v[44:45], off nt
	global_load_dword v87, v[56:57], off nt
	global_load_dword v88, v[46:47], off nt
	global_load_dword v89, v[58:59], off nt
	v_or_b32_e32 v46, s34, v3
	v_or_b32_e32 v44, s35, v2
	s_add_i32 s21, s21, 16
	s_add_i32 s20, s20, 16
	s_add_i32 s31, s31, -16
	v_mad_u64_u32 v[44:45], s[10:11], v44, s27, v[6:7]
	v_mad_u64_u32 v[46:47], s[10:11], v46, s27, v[6:7]
	v_or_b32_e32 v45, s36, v3
	v_or_b32_e32 v47, s37, v2
	v_or_b32_e32 v54, s38, v3
	v_or_b32_e32 v52, s39, v2
	v_or_b32_e32 v58, s40, v3
	v_or_b32_e32 v56, s41, v2
	v_or_b32_e32 v62, s42, v3
	v_or_b32_e32 v60, s43, v2
	v_or_b32_e32 v66, s44, v3
	v_or_b32_e32 v64, s45, v2
	v_or_b32_e32 v70, s46, v3
	v_or_b32_e32 v68, s47, v2
	v_or_b32_e32 v74, s48, v3
	v_or_b32_e32 v72, s49, v2
	s_cmp_lg_u32 s31, 0
	v_mad_u64_u32 v[48:49], s[10:11], v47, s27, v[6:7]
	v_mad_u64_u32 v[50:51], s[10:11], v45, s27, v[6:7]
	v_mad_u64_u32 v[52:53], s[10:11], v52, s27, v[6:7]
	v_mad_u64_u32 v[54:55], s[10:11], v54, s27, v[6:7]
	v_mad_u64_u32 v[56:57], s[10:11], v56, s27, v[6:7]
	v_mad_u64_u32 v[58:59], s[10:11], v58, s27, v[6:7]
	v_mad_u64_u32 v[60:61], s[10:11], v60, s27, v[6:7]
	v_mad_u64_u32 v[62:63], s[10:11], v62, s27, v[6:7]
	v_mad_u64_u32 v[64:65], s[10:11], v64, s27, v[6:7]
	v_mad_u64_u32 v[66:67], s[10:11], v66, s27, v[6:7]
	v_mad_u64_u32 v[68:69], s[10:11], v68, s27, v[6:7]
	v_mad_u64_u32 v[70:71], s[10:11], v70, s27, v[6:7]
	v_mad_u64_u32 v[72:73], s[10:11], v72, s27, v[6:7]
	v_mad_u64_u32 v[74:75], s[10:11], v74, s27, v[6:7]
	s_waitcnt vmcnt(15)
	ds_write_b32 v44, v35
	s_waitcnt vmcnt(14)
	ds_write_b32 v46, v76
	s_waitcnt vmcnt(13)
	ds_write_b32 v48, v77
	s_waitcnt vmcnt(12)
	ds_write_b32 v50, v78
	s_waitcnt vmcnt(11)
	ds_write_b32 v52, v79
	s_waitcnt vmcnt(10)
	ds_write_b32 v54, v80
	s_waitcnt vmcnt(9)
	ds_write_b32 v56, v81
	s_waitcnt vmcnt(8)
	ds_write_b32 v58, v82
	s_waitcnt vmcnt(7)
	ds_write_b32 v60, v83
	s_waitcnt vmcnt(6)
	ds_write_b32 v62, v84
	s_waitcnt vmcnt(5)
	ds_write_b32 v64, v85
	s_waitcnt vmcnt(4)
	ds_write_b32 v66, v86
	s_waitcnt vmcnt(3)
	ds_write_b32 v68, v0
	s_waitcnt vmcnt(2)
	ds_write_b32 v70, v87
	s_waitcnt vmcnt(1)
	ds_write_b32 v72, v88
	s_waitcnt vmcnt(0)
	ds_write_b32 v74, v89
	s_cbranch_scc1 .LBB0_46
; #define LAS __attribute__((address_space(3)))
; __device__ __forceinline__ unsigned pk2(float lo, float hi) { return f2bf(lo) | (f2bf(hi) << 16); }
; __device__ __forceinline__ void tr_item(const float* W, int ldw, int c0, bf16* WT, int ldk, int r0, int nblk, int item, LAS float* scr, int lane) {
;     ...
;     asm volatile("s_waitcnt lgkmcnt(0)" ::: "memory");
;     const int c = lane & 7;
; #pragma unroll
;     for (int j = 0; j < 4; ++j) { const int n = (lane >> 3) + 8 * j; const LAS float* s = scr + (8 * c) * 33 + n;
;         v4u o; o.x = pk2(s[0 * 33], s[1 * 33]); o.y = pk2(s[2 * 33], s[3 * 33]); o.z = pk2(s[4 * 33], s[5 * 33]); o.w = pk2(s[6 * 33], s[7 * 33]);
;         *(v4u*)(WT + (size_t)(r0 + n0 + n) * ldk + k0 + 8 * c) = o; }
;     asm volatile("s_waitcnt lgkmcnt(0)" ::: "memory");
	s_waitcnt lgkmcnt(0)
	ds_read2_b32 v[36:37], v40 offset1:8
	ds_read2_b32 v[50:51], v40 offset0:33 offset1:41
	ds_read2_b32 v[52:53], v40 offset0:66 offset1:74
	ds_read2_b32 v[54:55], v40 offset0:99 offset1:107
	ds_read2_b32 v[56:57], v40 offset0:132 offset1:140
	s_mov_b32 s85, 0xffff0000
	s_waitcnt lgkmcnt(4)
	v_bfe_u32 v0, v36, 16, 1
	v_add3_u32 v0, v36, v0, s80
	s_waitcnt lgkmcnt(3)
	v_bfe_u32 v7, v50, 16, 1
	v_lshrrev_b32_e32 v0, 16, v0
	v_add3_u32 v7, v50, v7, s80
	ds_read2_b32 v[58:59], v40 offset0:165 offset1:173
	v_and_or_b32 v44, v7, s85, v0
	s_waitcnt lgkmcnt(3)
	v_bfe_u32 v0, v52, 16, 1
	v_add3_u32 v0, v52, v0, s80
	s_waitcnt lgkmcnt(2)
	v_bfe_u32 v7, v54, 16, 1
	ds_read2_b32 v[60:61], v40 offset0:198 offset1:206
	v_lshrrev_b32_e32 v0, 16, v0
	v_add3_u32 v7, v54, v7, s80
	ds_read2_b32 v[62:63], v40 offset0:231 offset1:239
	v_and_or_b32 v45, v7, s85, v0
	s_waitcnt lgkmcnt(3)
	v_bfe_u32 v0, v56, 16, 1
	v_add3_u32 v0, v56, v0, s80
	s_waitcnt lgkmcnt(2)
	v_bfe_u32 v7, v58, 16, 1
	v_lshrrev_b32_e32 v0, 16, v0
	v_add3_u32 v7, v58, v7, s80
	v_and_or_b32 v46, v7, s85, v0
	s_waitcnt lgkmcnt(1)
	v_bfe_u32 v0, v60, 16, 1
	v_add3_u32 v0, v60, v0, s80
	s_waitcnt lgkmcnt(0)
	v_bfe_u32 v7, v62, 16, 1
	v_lshrrev_b32_e32 v0, 16, v0
	v_add3_u32 v7, v62, v7, s80
	s_lshl_b32 s88, s4, 1
	v_and_or_b32 v47, v7, s85, v0
	v_or_b32_e32 v0, s1, v39
	v_lshl_add_u64 v[48:49], v[18:19], 0, s[88:89]
	v_lshlrev_b32_e32 v0, 11, v0
	v_lshl_add_u64 v[64:65], v[48:49], 0, v[0:1]
	v_bfe_u32 v0, v37, 16, 1
	v_add3_u32 v0, v37, v0, s80
	v_bfe_u32 v7, v51, 16, 1
	v_lshrrev_b32_e32 v0, 16, v0
	v_add3_u32 v7, v51, v7, s80
	global_store_dwordx4 v[64:65], v[44:47], off
	ds_read2_b32 v[36:37], v40 offset0:16 offset1:24
	v_readlane_b32 s81, v254, 55
	v_and_or_b32 v44, v7, s85, v0
	v_bfe_u32 v0, v53, 16, 1
	v_add3_u32 v0, v53, v0, s80
	v_bfe_u32 v7, v55, 16, 1
	v_lshrrev_b32_e32 v0, 16, v0
	v_add3_u32 v7, v55, v7, s80
	v_and_or_b32 v45, v7, s85, v0
	v_bfe_u32 v0, v57, 16, 1
	v_add3_u32 v0, v57, v0, s80
	v_bfe_u32 v7, v59, 16, 1
	v_lshrrev_b32_e32 v0, 16, v0
	v_add3_u32 v7, v59, v7, s80
	v_and_or_b32 v46, v7, s85, v0
	v_bfe_u32 v0, v61, 16, 1
	v_add3_u32 v0, v61, v0, s80
	v_bfe_u32 v7, v63, 16, 1
	v_lshrrev_b32_e32 v0, 16, v0
	v_add3_u32 v7, v63, v7, s80
	v_and_or_b32 v47, v7, s85, v0
	v_or_b32_e32 v0, s1, v41
	v_lshlrev_b32_e32 v0, 11, v0
	v_lshl_add_u64 v[50:51], v[48:49], 0, v[0:1]
	global_store_dwordx4 v[50:51], v[44:47], off
	ds_read2_b32 v[50:51], v40 offset0:49 offset1:57
	ds_read2_b32 v[52:53], v40 offset0:82 offset1:90
	ds_read2_b32 v[54:55], v40 offset0:115 offset1:123
	s_waitcnt lgkmcnt(3)
	v_bfe_u32 v0, v36, 16, 1
	v_add3_u32 v0, v36, v0, s80
	s_waitcnt lgkmcnt(2)
	v_bfe_u32 v7, v50, 16, 1
	ds_read2_b32 v[56:57], v40 offset0:148 offset1:156
	v_lshrrev_b32_e32 v0, 16, v0
	v_add3_u32 v7, v50, v7, s80
	ds_read2_b32 v[58:59], v40 offset0:181 offset1:189
	v_and_or_b32 v44, v7, s85, v0
	s_waitcnt lgkmcnt(3)
	v_bfe_u32 v0, v52, 16, 1
	v_add3_u32 v0, v52, v0, s80
	s_waitcnt lgkmcnt(2)
	v_bfe_u32 v7, v54, 16, 1
	ds_read2_b32 v[60:61], v40 offset0:214 offset1:222
	v_lshrrev_b32_e32 v0, 16, v0
	v_add3_u32 v7, v54, v7, s80
	ds_read2_b32 v[62:63], v40 offset0:247 offset1:255
	v_and_or_b32 v45, v7, s85, v0
	s_waitcnt lgkmcnt(3)
	v_bfe_u32 v0, v56, 16, 1
	v_add3_u32 v0, v56, v0, s80
	s_waitcnt lgkmcnt(2)
	v_bfe_u32 v7, v58, 16, 1
	v_lshrrev_b32_e32 v0, 16, v0
	v_add3_u32 v7, v58, v7, s80
	v_and_or_b32 v46, v7, s85, v0
	s_waitcnt lgkmcnt(1)
	v_bfe_u32 v0, v60, 16, 1
	v_add3_u32 v0, v60, v0, s80
	s_waitcnt lgkmcnt(0)
	v_bfe_u32 v7, v62, 16, 1
	v_lshrrev_b32_e32 v0, 16, v0
	v_add3_u32 v7, v62, v7, s80
	v_and_or_b32 v47, v7, s85, v0
	v_or_b32_e32 v0, s1, v42
	v_lshlrev_b32_e32 v0, 11, v0
	v_lshl_add_u64 v[64:65], v[48:49], 0, v[0:1]
	v_bfe_u32 v0, v37, 16, 1
	v_add3_u32 v0, v37, v0, s80
	v_bfe_u32 v7, v51, 16, 1
	v_lshrrev_b32_e32 v0, 16, v0
	v_add3_u32 v7, v51, v7, s80
	global_store_dwordx4 v[64:65], v[44:47], off
	s_nop 1
	v_and_or_b32 v44, v7, s85, v0
	v_bfe_u32 v0, v53, 16, 1
	v_add3_u32 v0, v53, v0, s80
	v_bfe_u32 v7, v55, 16, 1
	v_lshrrev_b32_e32 v0, 16, v0
	v_add3_u32 v7, v55, v7, s80
	v_and_or_b32 v45, v7, s85, v0
	v_bfe_u32 v0, v57, 16, 1
	v_add3_u32 v0, v57, v0, s80
	v_bfe_u32 v7, v59, 16, 1
	v_lshrrev_b32_e32 v0, 16, v0
	v_add3_u32 v7, v59, v7, s80
	v_and_or_b32 v46, v7, s85, v0
	v_bfe_u32 v0, v61, 16, 1
	v_add3_u32 v0, v61, v0, s80
	v_bfe_u32 v7, v63, 16, 1
	v_lshrrev_b32_e32 v0, 16, v0
	v_add3_u32 v7, v63, v7, s80
	v_and_or_b32 v47, v7, s85, v0
	v_or_b32_e32 v0, s1, v43
	v_lshlrev_b32_e32 v0, 11, v0
	v_lshl_add_u64 v[36:37], v[48:49], 0, v[0:1]
	global_store_dwordx4 v[36:37], v[44:47], off
	s_waitcnt lgkmcnt(0)

; #define LAS __attribute__((address_space(3)))
; __device__ __forceinline__ void tr_item(const float* W, int ldw, int c0, bf16* WT, int ldk, int r0, int nblk, int item, LAS float* scr, int lane) {
;     const int kb = item / nblk, nb = item % nblk, k0 = 64 * kb, n0 = 32 * nb;
; #pragma unroll 8
;     for (int i = 0; i < 32; ++i) { const int kk = 2 * i + (lane >> 5); scr[kk * 33 + (lane & 31)] = W[(size_t)(k0 + kk) * ldw + c0 + n0 + (lane & 31)]; }
.LBB0_51:
	s_lshl_b32 s34, s20, 1
	s_lshl_b32 s35, s21, 1
	v_or_b32_e32 v0, s35, v38
	s_add_i32 s36, s34, 4
	s_add_i32 s37, s35, 4
	v_mov_b32_e32 v47, v1
	s_add_i32 s39, s35, 8
	v_lshlrev_b64 v[60:61], 12, v[0:1]
	v_or_b32_e32 v46, s36, v7
	v_or_b32_e32 v0, s37, v38
	v_mov_b32_e32 v45, v1
	v_or_b32_e32 v44, s34, v7
	s_add_i32 s41, s35, 12
	v_lshlrev_b64 v[46:47], 12, v[46:47]
	v_lshlrev_b64 v[62:63], 12, v[0:1]
	v_or_b32_e32 v0, s39, v38
	s_add_i32 s38, s34, 8
	s_add_i32 s40, s34, 12
	s_add_i32 s43, s35, 16
	v_lshlrev_b64 v[44:45], 12, v[44:45]
	v_lshl_add_u64 v[60:61], v[36:37], 0, v[60:61]
	v_lshl_add_u64 v[46:47], v[36:37], 0, v[46:47]
	v_lshlrev_b64 v[64:65], 12, v[0:1]
	v_or_b32_e32 v0, s41, v38
	v_mov_b32_e32 v49, v1
	v_mov_b32_e32 v51, v1
	s_add_i32 s45, s35, 20
	v_or_b32_e32 v48, s38, v7
	v_or_b32_e32 v50, s40, v7
	v_lshl_add_u64 v[44:45], v[36:37], 0, v[44:45]
	v_lshl_add_u64 v[62:63], v[36:37], 0, v[62:63]
	global_load_dword v35, v[60:61], off nt
	global_load_dword v76, v[44:45], off nt
	global_load_dword v77, v[62:63], off nt
	global_load_dword v78, v[46:47], off nt
	v_lshlrev_b64 v[46:47], 12, v[0:1]
	v_or_b32_e32 v0, s43, v38
	s_add_i32 s42, s34, 16
	s_add_i32 s44, s34, 20
	s_add_i32 s47, s35, 24
	v_lshlrev_b64 v[48:49], 12, v[48:49]
	v_lshlrev_b64 v[50:51], 12, v[50:51]
	v_lshl_add_u64 v[44:45], v[36:37], 0, v[64:65]
	v_lshl_add_u64 v[46:47], v[36:37], 0, v[46:47]
	v_lshlrev_b64 v[60:61], 12, v[0:1]
	v_or_b32_e32 v0, s45, v38
	v_mov_b32_e32 v53, v1
	v_mov_b32_e32 v55, v1
	s_add_i32 s46, s34, 24
	s_add_i32 s48, s34, 28
	s_add_i32 s49, s35, 28
	v_or_b32_e32 v52, s42, v7
	v_or_b32_e32 v54, s44, v7
	v_lshl_add_u64 v[48:49], v[36:37], 0, v[48:49]
	v_lshl_add_u64 v[50:51], v[36:37], 0, v[50:51]
	global_load_dword v79, v[44:45], off nt
	global_load_dword v80, v[48:49], off nt
	global_load_dword v81, v[46:47], off nt
	global_load_dword v82, v[50:51], off nt
	v_lshlrev_b64 v[46:47], 12, v[0:1]
	v_or_b32_e32 v0, s47, v38
	v_mov_b32_e32 v57, v1
	v_mov_b32_e32 v59, v1
	v_or_b32_e32 v56, s46, v7
	v_or_b32_e32 v58, s48, v7
	v_lshlrev_b64 v[52:53], 12, v[52:53]
	v_lshlrev_b64 v[54:55], 12, v[54:55]
	v_lshl_add_u64 v[44:45], v[36:37], 0, v[60:61]
	v_lshl_add_u64 v[46:47], v[36:37], 0, v[46:47]
	v_lshlrev_b64 v[48:49], 12, v[0:1]
	v_or_b32_e32 v0, s49, v38
	v_lshlrev_b64 v[56:57], 12, v[56:57]
	v_lshlrev_b64 v[58:59], 12, v[58:59]
	v_lshl_add_u64 v[52:53], v[36:37], 0, v[52:53]
	v_lshl_add_u64 v[54:55], v[36:37], 0, v[54:55]
	global_load_dword v83, v[44:45], off nt
	global_load_dword v84, v[52:53], off nt
	global_load_dword v85, v[46:47], off nt
	global_load_dword v86, v[54:55], off nt
	v_lshl_add_u64 v[44:45], v[36:37], 0, v[48:49]
	v_lshlrev_b64 v[46:47], 12, v[0:1]
	v_lshl_add_u64 v[56:57], v[36:37], 0, v[56:57]
	v_lshl_add_u64 v[58:59], v[36:37], 0, v[58:59]
	v_lshl_add_u64 v[46:47], v[36:37], 0, v[46:47]
	global_load_dword v0, v[44:45], off nt
	global_load_dword v87, v[56:57], off nt
	global_load_dword v88, v[46:47], off nt
	global_load_dword v89, v[58:59], off nt
	v_or_b32_e32 v46, s34, v3
	v_or_b32_e32 v44, s35, v2
	s_add_i32 s21, s21, 16
	s_add_i32 s20, s20, 16
	s_add_i32 s31, s31, -16
	v_mad_u64_u32 v[44:45], s[10:11], v44, s27, v[6:7]
	v_mad_u64_u32 v[46:47], s[10:11], v46, s27, v[6:7]
	v_or_b32_e32 v45, s36, v3
	v_or_b32_e32 v47, s37, v2
	v_or_b32_e32 v54, s38, v3
	v_or_b32_e32 v52, s39, v2
	v_or_b32_e32 v58, s40, v3
	v_or_b32_e32 v56, s41, v2
	v_or_b32_e32 v62, s42, v3
	v_or_b32_e32 v60, s43, v2
	v_or_b32_e32 v66, s44, v3
	v_or_b32_e32 v64, s45, v2
	v_or_b32_e32 v70, s46, v3
	v_or_b32_e32 v68, s47, v2
	v_or_b32_e32 v74, s48, v3
	v_or_b32_e32 v72, s49, v2
	s_cmp_lg_u32 s31, 0
	v_mad_u64_u32 v[48:49], s[10:11], v47, s27, v[6:7]
	v_mad_u64_u32 v[50:51], s[10:11], v45, s27, v[6:7]
	v_mad_u64_u32 v[52:53], s[10:11], v52, s27, v[6:7]
	v_mad_u64_u32 v[54:55], s[10:11], v54, s27, v[6:7]
	v_mad_u64_u32 v[56:57], s[10:11], v56, s27, v[6:7]
	v_mad_u64_u32 v[58:59], s[10:11], v58, s27, v[6:7]
	v_mad_u64_u32 v[60:61], s[10:11], v60, s27, v[6:7]
	v_mad_u64_u32 v[62:63], s[10:11], v62, s27, v[6:7]
	v_mad_u64_u32 v[64:65], s[10:11], v64, s27, v[6:7]
	v_mad_u64_u32 v[66:67], s[10:11], v66, s27, v[6:7]
	v_mad_u64_u32 v[68:69], s[10:11], v68, s27, v[6:7]
	v_mad_u64_u32 v[70:71], s[10:11], v70, s27, v[6:7]
	v_mad_u64_u32 v[72:73], s[10:11], v72, s27, v[6:7]
	v_mad_u64_u32 v[74:75], s[10:11], v74, s27, v[6:7]
	s_waitcnt vmcnt(15)
	ds_write_b32 v44, v35
	s_waitcnt vmcnt(14)
	ds_write_b32 v46, v76
	s_waitcnt vmcnt(13)
	ds_write_b32 v48, v77
	s_waitcnt vmcnt(12)
	ds_write_b32 v50, v78
	s_waitcnt vmcnt(11)
	ds_write_b32 v52, v79
	s_waitcnt vmcnt(10)
	ds_write_b32 v54, v80
	s_waitcnt vmcnt(9)
	ds_write_b32 v56, v81
	s_waitcnt vmcnt(8)
	ds_write_b32 v58, v82
	s_waitcnt vmcnt(7)
	ds_write_b32 v60, v83
	s_waitcnt vmcnt(6)
	ds_write_b32 v62, v84
	s_waitcnt vmcnt(5)
	ds_write_b32 v64, v85
	s_waitcnt vmcnt(4)
	ds_write_b32 v66, v86
	s_waitcnt vmcnt(3)
	ds_write_b32 v68, v0
	s_waitcnt vmcnt(2)
	ds_write_b32 v70, v87
	s_waitcnt vmcnt(1)
	ds_write_b32 v72, v88
	s_waitcnt vmcnt(0)
	ds_write_b32 v74, v89
	s_cbranch_scc1 .LBB0_51
; #define LAS __attribute__((address_space(3)))
; __device__ __forceinline__ unsigned pk2(float lo, float hi) { return f2bf(lo) | (f2bf(hi) << 16); }
; __device__ __forceinline__ void tr_item(const float* W, int ldw, int c0, bf16* WT, int ldk, int r0, int nblk, int item, LAS float* scr, int lane) {
;     ...
;     asm volatile("s_waitcnt lgkmcnt(0)" ::: "memory");
;     const int c = lane & 7;
; #pragma unroll
;     for (int j = 0; j < 4; ++j) { const int n = (lane >> 3) + 8 * j; const LAS float* s = scr + (8 * c) * 33 + n;
;         v4u o; o.x = pk2(s[0 * 33], s[1 * 33]); o.y = pk2(s[2 * 33], s[3 * 33]); o.z = pk2(s[4 * 33], s[5 * 33]); o.w = pk2(s[6 * 33], s[7 * 33]);
;         *(v4u*)(WT + (size_t)(r0 + n0 + n) * ldk + k0 + 8 * c) = o; }
;     asm volatile("s_waitcnt lgkmcnt(0)" ::: "memory");
; __device__ __forceinline__ void phase_convert_weights(const Ctx& C0, const Params& p, int l) {
;     ...
;         if (r < I_B) { const int n = r / 256, s = r % 256; tr_item(w_br + (size_t)n * 512 * 1024, 1024, 0, W + WO_B + (size_t)n * 1024 * 512, 512, 0, 32, s, scr, C.lane); continue; } r -= I_B;
	s_waitcnt lgkmcnt(0)
	s_lshl_b64 s[10:11], s[88:89], 20
	v_readlane_b32 s13, v251, 39
	ds_read2_b32 v[36:37], v40 offset1:8
	s_add_u32 s10, s13, s10
	v_readlane_b32 s13, v251, 40
	ds_read2_b32 v[50:51], v40 offset0:33 offset1:41
	s_addc_u32 s11, s13, s11
	s_lshl_b32 s4, s4, 1
	s_add_u32 s10, s10, s4
	ds_read2_b32 v[52:53], v40 offset0:66 offset1:74
	s_addc_u32 s11, s11, 0
	v_lshlrev_b32_e32 v0, 1, v8
	ds_read2_b32 v[54:55], v40 offset0:99 offset1:107
	v_lshl_add_u64 v[48:49], s[10:11], 0, v[0:1]
	s_waitcnt lgkmcnt(3)
	v_bfe_u32 v0, v36, 16, 1
	v_add3_u32 v0, v36, v0, s80
	s_waitcnt lgkmcnt(2)
	v_bfe_u32 v7, v50, 16, 1
	ds_read2_b32 v[56:57], v40 offset0:132 offset1:140
	v_lshrrev_b32_e32 v0, 16, v0
	v_add3_u32 v7, v50, v7, s80
	s_mov_b32 s85, 0xffff0000
	ds_read2_b32 v[58:59], v40 offset0:165 offset1:173
	v_and_or_b32 v44, v7, s85, v0
	s_waitcnt lgkmcnt(3)
	v_bfe_u32 v0, v52, 16, 1
	v_add3_u32 v0, v52, v0, s80
	s_waitcnt lgkmcnt(2)
	v_bfe_u32 v7, v54, 16, 1
	ds_read2_b32 v[60:61], v40 offset0:198 offset1:206
	v_lshrrev_b32_e32 v0, 16, v0
	v_add3_u32 v7, v54, v7, s80
	ds_read2_b32 v[62:63], v40 offset0:231 offset1:239
	v_and_or_b32 v45, v7, s85, v0
	s_waitcnt lgkmcnt(3)
	v_bfe_u32 v0, v56, 16, 1
	v_add3_u32 v0, v56, v0, s80
	s_waitcnt lgkmcnt(2)
	v_bfe_u32 v7, v58, 16, 1
	v_lshrrev_b32_e32 v0, 16, v0
	v_add3_u32 v7, v58, v7, s80
	v_and_or_b32 v46, v7, s85, v0
	s_waitcnt lgkmcnt(1)
	v_bfe_u32 v0, v60, 16, 1
	v_add3_u32 v0, v60, v0, s80
	s_waitcnt lgkmcnt(0)
	v_bfe_u32 v7, v62, 16, 1
	v_lshrrev_b32_e32 v0, 16, v0
	v_add3_u32 v7, v62, v7, s80
	v_and_or_b32 v47, v7, s85, v0
	v_or_b32_e32 v0, s1, v39
	v_lshlrev_b32_e32 v0, 10, v0
	v_lshl_add_u64 v[64:65], v[48:49], 0, v[0:1]
	v_bfe_u32 v0, v37, 16, 1
	v_add3_u32 v0, v37, v0, s80
	v_bfe_u32 v7, v51, 16, 1
	v_lshrrev_b32_e32 v0, 16, v0
	v_add3_u32 v7, v51, v7, s80
	global_store_dwordx4 v[64:65], v[44:47], off
	ds_read2_b32 v[36:37], v40 offset0:16 offset1:24
	v_readlane_b32 s81, v254, 55
	v_and_or_b32 v44, v7, s85, v0
	v_bfe_u32 v0, v53, 16, 1
	v_add3_u32 v0, v53, v0, s80
	v_bfe_u32 v7, v55, 16, 1
	v_lshrrev_b32_e32 v0, 16, v0
	v_add3_u32 v7, v55, v7, s80
	v_and_or_b32 v45, v7, s85, v0
	v_bfe_u32 v0, v57, 16, 1
	v_add3_u32 v0, v57, v0, s80
	v_bfe_u32 v7, v59, 16, 1
	v_lshrrev_b32_e32 v0, 16, v0
	v_add3_u32 v7, v59, v7, s80
	v_and_or_b32 v46, v7, s85, v0
	v_bfe_u32 v0, v61, 16, 1
	v_add3_u32 v0, v61, v0, s80
	v_bfe_u32 v7, v63, 16, 1
	v_lshrrev_b32_e32 v0, 16, v0
	v_add3_u32 v7, v63, v7, s80
	v_and_or_b32 v47, v7, s85, v0
	v_or_b32_e32 v0, s1, v41
	v_lshlrev_b32_e32 v0, 10, v0
	v_lshl_add_u64 v[50:51], v[48:49], 0, v[0:1]
	global_store_dwordx4 v[50:51], v[44:47], off
	ds_read2_b32 v[50:51], v40 offset0:49 offset1:57
	ds_read2_b32 v[52:53], v40 offset0:82 offset1:90
	ds_read2_b32 v[54:55], v40 offset0:115 offset1:123
	s_waitcnt lgkmcnt(3)
	v_bfe_u32 v0, v36, 16, 1
	v_add3_u32 v0, v36, v0, s80
	s_waitcnt lgkmcnt(2)
	v_bfe_u32 v7, v50, 16, 1
	ds_read2_b32 v[56:57], v40 offset0:148 offset1:156
	v_lshrrev_b32_e32 v0, 16, v0
	v_add3_u32 v7, v50, v7, s80
	ds_read2_b32 v[58:59], v40 offset0:181 offset1:189
	v_and_or_b32 v44, v7, s85, v0
	s_waitcnt lgkmcnt(3)
	v_bfe_u32 v0, v52, 16, 1
	v_add3_u32 v0, v52, v0, s80
	s_waitcnt lgkmcnt(2)
	v_bfe_u32 v7, v54, 16, 1
	ds_read2_b32 v[60:61], v40 offset0:214 offset1:222
	v_lshrrev_b32_e32 v0, 16, v0
	v_add3_u32 v7, v54, v7, s80
	ds_read2_b32 v[62:63], v40 offset0:247 offset1:255
	v_and_or_b32 v45, v7, s85, v0
	s_waitcnt lgkmcnt(3)
	v_bfe_u32 v0, v56, 16, 1
	v_add3_u32 v0, v56, v0, s80
	s_waitcnt lgkmcnt(2)
	v_bfe_u32 v7, v58, 16, 1
	v_lshrrev_b32_e32 v0, 16, v0
	v_add3_u32 v7, v58, v7, s80
	v_and_or_b32 v46, v7, s85, v0
	s_waitcnt lgkmcnt(1)
	v_bfe_u32 v0, v60, 16, 1
	v_add3_u32 v0, v60, v0, s80
	s_waitcnt lgkmcnt(0)
	v_bfe_u32 v7, v62, 16, 1
	v_lshrrev_b32_e32 v0, 16, v0
	v_add3_u32 v7, v62, v7, s80
	v_and_or_b32 v47, v7, s85, v0
	v_or_b32_e32 v0, s1, v42
	v_lshlrev_b32_e32 v0, 10, v0
	v_lshl_add_u64 v[64:65], v[48:49], 0, v[0:1]
	v_bfe_u32 v0, v37, 16, 1
	v_add3_u32 v0, v37, v0, s80
	v_bfe_u32 v7, v51, 16, 1
	v_lshrrev_b32_e32 v0, 16, v0
	v_add3_u32 v7, v51, v7, s80
	global_store_dwordx4 v[64:65], v[44:47], off
	s_nop 1
	v_and_or_b32 v44, v7, s85, v0
	v_bfe_u32 v0, v53, 16, 1
	v_add3_u32 v0, v53, v0, s80
	v_bfe_u32 v7, v55, 16, 1
	v_lshrrev_b32_e32 v0, 16, v0
	v_add3_u32 v7, v55, v7, s80
	v_and_or_b32 v45, v7, s85, v0
	v_bfe_u32 v0, v57, 16, 1
	v_add3_u32 v0, v57, v0, s80
	v_bfe_u32 v7, v59, 16, 1
	v_lshrrev_b32_e32 v0, 16, v0
	v_add3_u32 v7, v59, v7, s80
	v_and_or_b32 v46, v7, s85, v0
	v_bfe_u32 v0, v61, 16, 1
	v_add3_u32 v0, v61, v0, s80
	v_bfe_u32 v7, v63, 16, 1
	v_lshrrev_b32_e32 v0, 16, v0
	v_add3_u32 v7, v63, v7, s80
	v_and_or_b32 v47, v7, s85, v0
	v_or_b32_e32 v0, s1, v43
	v_lshlrev_b32_e32 v0, 10, v0
	v_lshl_add_u64 v[36:37], v[48:49], 0, v[0:1]
	global_store_dwordx4 v[36:37], v[44:47], off
	s_waitcnt lgkmcnt(0)

; #define LAS __attribute__((address_space(3)))
; __device__ __forceinline__ void tr_item(const float* W, int ldw, int c0, bf16* WT, int ldk, int r0, int nblk, int item, LAS float* scr, int lane) {
;     const int kb = item / nblk, nb = item % nblk, k0 = 64 * kb, n0 = 32 * nb;
; #pragma unroll 8
;     for (int i = 0; i < 32; ++i) { const int kk = 2 * i + (lane >> 5); scr[kk * 33 + (lane & 31)] = W[(size_t)(k0 + kk) * ldw + c0 + n0 + (lane & 31)]; }
.LBB0_56:
	s_lshl_b32 s35, s21, 1
	s_lshl_b32 s36, s31, 1
	v_or_b32_e32 v0, s36, v38
	s_add_i32 s37, s35, 4
	s_add_i32 s38, s36, 4
	v_mov_b32_e32 v47, v1
	s_add_i32 s40, s36, 8
	v_lshlrev_b64 v[60:61], 12, v[0:1]
	v_or_b32_e32 v46, s37, v7
	v_or_b32_e32 v0, s38, v38
	v_mov_b32_e32 v45, v1
	v_or_b32_e32 v44, s35, v7
	s_add_i32 s42, s36, 12
	v_lshlrev_b64 v[46:47], 12, v[46:47]
	v_lshlrev_b64 v[62:63], 12, v[0:1]
	v_or_b32_e32 v0, s40, v38
	s_add_i32 s39, s35, 8
	s_add_i32 s41, s35, 12
	s_add_i32 s44, s36, 16
	v_lshlrev_b64 v[44:45], 12, v[44:45]
	v_lshl_add_u64 v[60:61], v[36:37], 0, v[60:61]
	v_lshl_add_u64 v[46:47], v[36:37], 0, v[46:47]
	v_lshlrev_b64 v[64:65], 12, v[0:1]
	v_or_b32_e32 v0, s42, v38
	v_mov_b32_e32 v49, v1
	v_mov_b32_e32 v51, v1
	s_add_i32 s46, s36, 20
	v_or_b32_e32 v48, s39, v7
	v_or_b32_e32 v50, s41, v7
	v_lshl_add_u64 v[44:45], v[36:37], 0, v[44:45]
	v_lshl_add_u64 v[62:63], v[36:37], 0, v[62:63]
	global_load_dword v35, v[60:61], off nt
	global_load_dword v76, v[44:45], off nt
	global_load_dword v77, v[62:63], off nt
	global_load_dword v78, v[46:47], off nt
	v_lshlrev_b64 v[46:47], 12, v[0:1]
	v_or_b32_e32 v0, s44, v38
	s_add_i32 s43, s35, 16
	s_add_i32 s45, s35, 20
	s_add_i32 s48, s36, 24
	v_lshlrev_b64 v[48:49], 12, v[48:49]
	v_lshlrev_b64 v[50:51], 12, v[50:51]
	v_lshl_add_u64 v[44:45], v[36:37], 0, v[64:65]
	v_lshl_add_u64 v[46:47], v[36:37], 0, v[46:47]
	v_lshlrev_b64 v[60:61], 12, v[0:1]
	v_or_b32_e32 v0, s46, v38
	v_mov_b32_e32 v53, v1
	v_mov_b32_e32 v55, v1
	s_add_i32 s47, s35, 24
	s_add_i32 s49, s35, 28
	s_add_i32 s50, s36, 28
	v_or_b32_e32 v52, s43, v7
	v_or_b32_e32 v54, s45, v7
	v_lshl_add_u64 v[48:49], v[36:37], 0, v[48:49]
	v_lshl_add_u64 v[50:51], v[36:37], 0, v[50:51]
	global_load_dword v79, v[44:45], off nt
	global_load_dword v80, v[48:49], off nt
	global_load_dword v81, v[46:47], off nt
	global_load_dword v82, v[50:51], off nt
	v_lshlrev_b64 v[46:47], 12, v[0:1]
	v_or_b32_e32 v0, s48, v38
	v_mov_b32_e32 v57, v1
	v_mov_b32_e32 v59, v1
	v_or_b32_e32 v56, s47, v7
	v_or_b32_e32 v58, s49, v7
	v_lshlrev_b64 v[52:53], 12, v[52:53]
	v_lshlrev_b64 v[54:55], 12, v[54:55]
	v_lshl_add_u64 v[44:45], v[36:37], 0, v[60:61]
	v_lshl_add_u64 v[46:47], v[36:37], 0, v[46:47]
	v_lshlrev_b64 v[48:49], 12, v[0:1]
	v_or_b32_e32 v0, s50, v38
	v_lshlrev_b64 v[56:57], 12, v[56:57]
	v_lshlrev_b64 v[58:59], 12, v[58:59]
	v_lshl_add_u64 v[52:53], v[36:37], 0, v[52:53]
	v_lshl_add_u64 v[54:55], v[36:37], 0, v[54:55]
	global_load_dword v83, v[44:45], off nt
	global_load_dword v84, v[52:53], off nt
	global_load_dword v85, v[46:47], off nt
	global_load_dword v86, v[54:55], off nt
	v_lshl_add_u64 v[44:45], v[36:37], 0, v[48:49]
	v_lshlrev_b64 v[46:47], 12, v[0:1]
	v_lshl_add_u64 v[56:57], v[36:37], 0, v[56:57]
	v_lshl_add_u64 v[58:59], v[36:37], 0, v[58:59]
	v_lshl_add_u64 v[46:47], v[36:37], 0, v[46:47]
	global_load_dword v0, v[44:45], off nt
	global_load_dword v87, v[56:57], off nt
	global_load_dword v88, v[46:47], off nt
	global_load_dword v89, v[58:59], off nt
	v_or_b32_e32 v46, s35, v3
	v_or_b32_e32 v44, s36, v2
	s_add_i32 s31, s31, 16
	s_add_i32 s21, s21, 16
	s_add_i32 s34, s34, -16
	v_mad_u64_u32 v[44:45], s[10:11], v44, s27, v[6:7]
	v_mad_u64_u32 v[46:47], s[10:11], v46, s27, v[6:7]
	v_or_b32_e32 v45, s37, v3
	v_or_b32_e32 v47, s38, v2
	v_or_b32_e32 v54, s39, v3
	v_or_b32_e32 v52, s40, v2
	v_or_b32_e32 v58, s41, v3
	v_or_b32_e32 v56, s42, v2
	v_or_b32_e32 v62, s43, v3
	v_or_b32_e32 v60, s44, v2
	v_or_b32_e32 v66, s45, v3
	v_or_b32_e32 v64, s46, v2
	v_or_b32_e32 v70, s47, v3
	v_or_b32_e32 v68, s48, v2
	v_or_b32_e32 v74, s49, v3
	v_or_b32_e32 v72, s50, v2
	s_cmp_lg_u32 s34, 0
	v_mad_u64_u32 v[48:49], s[10:11], v47, s27, v[6:7]
	v_mad_u64_u32 v[50:51], s[10:11], v45, s27, v[6:7]
	v_mad_u64_u32 v[52:53], s[10:11], v52, s27, v[6:7]
	v_mad_u64_u32 v[54:55], s[10:11], v54, s27, v[6:7]
	v_mad_u64_u32 v[56:57], s[10:11], v56, s27, v[6:7]
	v_mad_u64_u32 v[58:59], s[10:11], v58, s27, v[6:7]
	v_mad_u64_u32 v[60:61], s[10:11], v60, s27, v[6:7]
	v_mad_u64_u32 v[62:63], s[10:11], v62, s27, v[6:7]
	v_mad_u64_u32 v[64:65], s[10:11], v64, s27, v[6:7]
	v_mad_u64_u32 v[66:67], s[10:11], v66, s27, v[6:7]
	v_mad_u64_u32 v[68:69], s[10:11], v68, s27, v[6:7]
	v_mad_u64_u32 v[70:71], s[10:11], v70, s27, v[6:7]
	v_mad_u64_u32 v[72:73], s[10:11], v72, s27, v[6:7]
	v_mad_u64_u32 v[74:75], s[10:11], v74, s27, v[6:7]
	s_waitcnt vmcnt(15)
	ds_write_b32 v44, v35
	s_waitcnt vmcnt(14)
	ds_write_b32 v46, v76
	s_waitcnt vmcnt(13)
	ds_write_b32 v48, v77
	s_waitcnt vmcnt(12)
	ds_write_b32 v50, v78
	s_waitcnt vmcnt(11)
	ds_write_b32 v52, v79
	s_waitcnt vmcnt(10)
	ds_write_b32 v54, v80
	s_waitcnt vmcnt(9)
	ds_write_b32 v56, v81
	s_waitcnt vmcnt(8)
	ds_write_b32 v58, v82
	s_waitcnt vmcnt(7)
	ds_write_b32 v60, v83
	s_waitcnt vmcnt(6)
	ds_write_b32 v62, v84
	s_waitcnt vmcnt(5)
	ds_write_b32 v64, v85
	s_waitcnt vmcnt(4)
	ds_write_b32 v66, v86
	s_waitcnt vmcnt(3)
	ds_write_b32 v68, v0
	s_waitcnt vmcnt(2)
	ds_write_b32 v70, v87
	s_waitcnt vmcnt(1)
	ds_write_b32 v72, v88
	s_waitcnt vmcnt(0)
	ds_write_b32 v74, v89
	s_cbranch_scc1 .LBB0_56
; #define LAS __attribute__((address_space(3)))
; __device__ __forceinline__ unsigned pk2(float lo, float hi) { return f2bf(lo) | (f2bf(hi) << 16); }
; __device__ __forceinline__ void tr_item(const float* W, int ldw, int c0, bf16* WT, int ldk, int r0, int nblk, int item, LAS float* scr, int lane) {
;     ...
;     asm volatile("s_waitcnt lgkmcnt(0)" ::: "memory");
;     const int c = lane & 7;
; #pragma unroll
;     for (int j = 0; j < 4; ++j) { const int n = (lane >> 3) + 8 * j; const LAS float* s = scr + (8 * c) * 33 + n;
;         v4u o; o.x = pk2(s[0 * 33], s[1 * 33]); o.y = pk2(s[2 * 33], s[3 * 33]); o.z = pk2(s[4 * 33], s[5 * 33]); o.w = pk2(s[6 * 33], s[7 * 33]);
;         *(v4u*)(WT + (size_t)(r0 + n0 + n) * ldk + k0 + 8 * c) = o; }
;     asm volatile("s_waitcnt lgkmcnt(0)" ::: "memory");
; __device__ __forceinline__ void phase_convert_weights(const Ctx& C0, const Params& p, int l) {
;     ...
;         if (r < I_KV) { const int job = r >> 2, sub = r & 3, h = job >> 1, part = job & 1;
;             tr_item(w_kvup, 1024, h * 128 + part * 64, W + (part ? WO_V : WO_K), 256, h * 64, 2, sub, scr, C.lane); continue; } r -= I_KV;
	s_cmp_eq_u32 s20, 0
	s_mov_b32 s10, 0xae0000
	s_cselect_b32 s10, s10, 0xb20000
	v_readlane_b32 s20, v252, 44
	s_waitcnt lgkmcnt(0)
	v_readlane_b32 s21, v252, 45
	s_add_u32 s10, s20, s10
	ds_read2_b32 v[36:37], v40 offset1:8
	s_addc_u32 s11, s21, 0
	s_lshl_b32 s1, s1, 6
	ds_read2_b32 v[50:51], v40 offset0:33 offset1:41
	s_add_i32 s1, s1, s0
	s_lshl_b32 s4, s4, 1
	s_add_u32 s10, s10, s4
	ds_read2_b32 v[52:53], v40 offset0:66 offset1:74
	s_addc_u32 s11, s11, 0
	v_lshlrev_b32_e32 v0, 1, v8
	ds_read2_b32 v[54:55], v40 offset0:99 offset1:107
	v_lshl_add_u64 v[48:49], s[10:11], 0, v[0:1]
	s_waitcnt lgkmcnt(3)
	v_bfe_u32 v0, v36, 16, 1
	v_add3_u32 v0, v36, v0, s80
	s_waitcnt lgkmcnt(2)
	v_bfe_u32 v7, v50, 16, 1
	ds_read2_b32 v[56:57], v40 offset0:132 offset1:140
	v_lshrrev_b32_e32 v0, 16, v0
	v_add3_u32 v7, v50, v7, s80
	s_mov_b32 s85, 0xffff0000
	ds_read2_b32 v[58:59], v40 offset0:165 offset1:173
	v_and_or_b32 v44, v7, s85, v0
	s_waitcnt lgkmcnt(3)
	v_bfe_u32 v0, v52, 16, 1
	v_add3_u32 v0, v52, v0, s80
	s_waitcnt lgkmcnt(2)
	v_bfe_u32 v7, v54, 16, 1
	ds_read2_b32 v[60:61], v40 offset0:198 offset1:206
	v_lshrrev_b32_e32 v0, 16, v0
	v_add3_u32 v7, v54, v7, s80
	ds_read2_b32 v[62:63], v40 offset0:231 offset1:239
	v_and_or_b32 v45, v7, s85, v0
	s_waitcnt lgkmcnt(3)
	v_bfe_u32 v0, v56, 16, 1
	v_add3_u32 v0, v56, v0, s80
	s_waitcnt lgkmcnt(2)
	v_bfe_u32 v7, v58, 16, 1
	v_lshrrev_b32_e32 v0, 16, v0
	v_add3_u32 v7, v58, v7, s80
	v_and_or_b32 v46, v7, s85, v0
	s_waitcnt lgkmcnt(1)
	v_bfe_u32 v0, v60, 16, 1
	v_add3_u32 v0, v60, v0, s80
	s_waitcnt lgkmcnt(0)
	v_bfe_u32 v7, v62, 16, 1
	v_lshrrev_b32_e32 v0, 16, v0
	v_add3_u32 v7, v62, v7, s80
	v_or_b32_e32 v64, s1, v39
	v_and_or_b32 v47, v7, s85, v0
	v_ashrrev_i32_e32 v65, 31, v64
	v_bfe_u32 v0, v37, 16, 1
	v_lshlrev_b64 v[64:65], 9, v[64:65]
	v_add3_u32 v0, v37, v0, s80
	v_bfe_u32 v7, v51, 16, 1
	v_lshl_add_u64 v[64:65], v[48:49], 0, v[64:65]
	v_lshrrev_b32_e32 v0, 16, v0
	v_add3_u32 v7, v51, v7, s80
	global_store_dwordx4 v[64:65], v[44:47], off
	v_or_b32_e32 v36, s1, v41
	v_ashrrev_i32_e32 v37, 31, v36
	v_and_or_b32 v44, v7, s85, v0
	v_bfe_u32 v0, v53, 16, 1
	v_add3_u32 v0, v53, v0, s80
	v_bfe_u32 v7, v55, 16, 1
	v_lshrrev_b32_e32 v0, 16, v0
	v_add3_u32 v7, v55, v7, s80
	v_and_or_b32 v45, v7, s85, v0
	v_bfe_u32 v0, v57, 16, 1
	v_add3_u32 v0, v57, v0, s80
	v_bfe_u32 v7, v59, 16, 1
	v_lshrrev_b32_e32 v0, 16, v0
	v_add3_u32 v7, v59, v7, s80
	v_and_or_b32 v46, v7, s85, v0
	v_bfe_u32 v0, v61, 16, 1
	v_add3_u32 v0, v61, v0, s80
	v_bfe_u32 v7, v63, 16, 1
	v_lshrrev_b32_e32 v0, 16, v0
	v_add3_u32 v7, v63, v7, s80
	v_lshlrev_b64 v[36:37], 9, v[36:37]
	v_and_or_b32 v47, v7, s85, v0
	ds_read2_b32 v[50:51], v40 offset0:16 offset1:24
	v_lshl_add_u64 v[36:37], v[48:49], 0, v[36:37]
	global_store_dwordx4 v[36:37], v[44:47], off
	ds_read2_b32 v[36:37], v40 offset0:49 offset1:57
	ds_read2_b32 v[52:53], v40 offset0:82 offset1:90
	ds_read2_b32 v[54:55], v40 offset0:115 offset1:123
	s_waitcnt lgkmcnt(3)
	v_bfe_u32 v0, v50, 16, 1
	v_add3_u32 v0, v50, v0, s80
	s_waitcnt lgkmcnt(2)
	v_bfe_u32 v7, v36, 16, 1
	ds_read2_b32 v[56:57], v40 offset0:148 offset1:156
	v_lshrrev_b32_e32 v0, 16, v0
	v_add3_u32 v7, v36, v7, s80
	ds_read2_b32 v[58:59], v40 offset0:181 offset1:189
	v_and_or_b32 v44, v7, s85, v0
	s_waitcnt lgkmcnt(3)
	v_bfe_u32 v0, v52, 16, 1
	v_add3_u32 v0, v52, v0, s80
	s_waitcnt lgkmcnt(2)
	v_bfe_u32 v7, v54, 16, 1
	ds_read2_b32 v[60:61], v40 offset0:214 offset1:222
	v_lshrrev_b32_e32 v0, 16, v0
	v_add3_u32 v7, v54, v7, s80
	ds_read2_b32 v[62:63], v40 offset0:247 offset1:255
	v_and_or_b32 v45, v7, s85, v0
	s_waitcnt lgkmcnt(3)
	v_bfe_u32 v0, v56, 16, 1
	v_add3_u32 v0, v56, v0, s80
	s_waitcnt lgkmcnt(2)
	v_bfe_u32 v7, v58, 16, 1
	v_lshrrev_b32_e32 v0, 16, v0
	v_add3_u32 v7, v58, v7, s80
	v_and_or_b32 v46, v7, s85, v0
	s_waitcnt lgkmcnt(1)
	v_bfe_u32 v0, v60, 16, 1
	v_add3_u32 v0, v60, v0, s80
	s_waitcnt lgkmcnt(0)
	v_bfe_u32 v7, v62, 16, 1
	v_lshrrev_b32_e32 v0, 16, v0
	v_add3_u32 v7, v62, v7, s80
	v_or_b32_e32 v64, s1, v42
	v_and_or_b32 v47, v7, s85, v0
	v_ashrrev_i32_e32 v65, 31, v64
	v_bfe_u32 v0, v51, 16, 1
	v_lshlrev_b64 v[64:65], 9, v[64:65]
	v_add3_u32 v0, v51, v0, s80
	v_bfe_u32 v7, v37, 16, 1
	v_lshl_add_u64 v[64:65], v[48:49], 0, v[64:65]
	v_lshrrev_b32_e32 v0, 16, v0
	v_add3_u32 v7, v37, v7, s80
	global_store_dwordx4 v[64:65], v[44:47], off
	v_or_b32_e32 v36, s1, v43
	v_ashrrev_i32_e32 v37, 31, v36
	v_and_or_b32 v44, v7, s85, v0
	v_bfe_u32 v0, v53, 16, 1
	v_add3_u32 v0, v53, v0, s80
	v_bfe_u32 v7, v55, 16, 1
	v_lshrrev_b32_e32 v0, 16, v0
	v_add3_u32 v7, v55, v7, s80
	v_and_or_b32 v45, v7, s85, v0
	v_bfe_u32 v0, v57, 16, 1
	v_add3_u32 v0, v57, v0, s80
	v_bfe_u32 v7, v59, 16, 1
	v_lshrrev_b32_e32 v0, 16, v0
	v_add3_u32 v7, v59, v7, s80
	v_and_or_b32 v46, v7, s85, v0
	v_bfe_u32 v0, v61, 16, 1
	v_add3_u32 v0, v61, v0, s80
	v_bfe_u32 v7, v63, 16, 1
	v_lshrrev_b32_e32 v0, 16, v0
	v_add3_u32 v7, v63, v7, s80
	v_lshlrev_b64 v[36:37], 9, v[36:37]
	v_and_or_b32 v47, v7, s85, v0
	v_lshl_add_u64 v[36:37], v[48:49], 0, v[36:37]
	global_store_dwordx4 v[36:37], v[44:47], off
	s_waitcnt lgkmcnt(0)
	v_readlane_b32 s81, v254, 55

; #define LAS __attribute__((address_space(3)))
; __device__ __forceinline__ void tr_item(const float* W, int ldw, int c0, bf16* WT, int ldk, int r0, int nblk, int item, LAS float* scr, int lane) {
;     const int kb = item / nblk, nb = item % nblk, k0 = 64 * kb, n0 = 32 * nb;
; #pragma unroll 8
;     for (int i = 0; i < 32; ++i) { const int kk = 2 * i + (lane >> 5); scr[kk * 33 + (lane & 31)] = W[(size_t)(k0 + kk) * ldw + c0 + n0 + (lane & 31)]; }
.LBB0_61:
	s_lshl_b32 s34, s20, 1
	s_lshl_b32 s35, s21, 1
	v_or_b32_e32 v35, s34, v7
	v_or_b32_e32 v38, s35, v0
	s_add_i32 s36, s34, 4
	s_add_i32 s37, s35, 4
	s_add_i32 s38, s34, 8
	s_add_i32 s39, s35, 8
	s_add_i32 s40, s34, 12
	s_add_i32 s41, s35, 12
	s_add_i32 s42, s34, 16
	s_add_i32 s43, s35, 16
	s_add_i32 s44, s34, 20
	s_add_i32 s45, s35, 20
	s_add_i32 s46, s34, 24
	s_add_i32 s47, s35, 24
	s_add_i32 s48, s34, 28
	s_add_i32 s49, s35, 28
	v_mad_u64_u32 v[44:45], s[10:11], v38, s82, v[36:37]
	v_mad_u64_u32 v[46:47], s[10:11], v35, s82, v[36:37]
	v_or_b32_e32 v35, s36, v7
	v_or_b32_e32 v38, s37, v0
	v_or_b32_e32 v54, s38, v7
	v_or_b32_e32 v52, s39, v0
	v_or_b32_e32 v58, s40, v7
	v_or_b32_e32 v56, s41, v0
	v_or_b32_e32 v62, s42, v7
	v_or_b32_e32 v60, s43, v0
	v_or_b32_e32 v66, s44, v7
	v_or_b32_e32 v64, s45, v0
	v_or_b32_e32 v70, s46, v7
	v_or_b32_e32 v68, s47, v0
	v_or_b32_e32 v74, s48, v7
	v_or_b32_e32 v72, s49, v0
	v_mad_u64_u32 v[48:49], s[10:11], v38, s82, v[36:37]
	v_mad_u64_u32 v[50:51], s[10:11], v35, s82, v[36:37]
	v_mad_u64_u32 v[52:53], s[10:11], v52, s82, v[36:37]
	v_mad_u64_u32 v[54:55], s[10:11], v54, s82, v[36:37]
	v_mad_u64_u32 v[56:57], s[10:11], v56, s82, v[36:37]
	v_mad_u64_u32 v[58:59], s[10:11], v58, s82, v[36:37]
	v_mad_u64_u32 v[60:61], s[10:11], v60, s82, v[36:37]
	v_mad_u64_u32 v[62:63], s[10:11], v62, s82, v[36:37]
	v_mad_u64_u32 v[64:65], s[10:11], v64, s82, v[36:37]
	v_mad_u64_u32 v[66:67], s[10:11], v66, s82, v[36:37]
	v_mad_u64_u32 v[68:69], s[10:11], v68, s82, v[36:37]
	v_mad_u64_u32 v[70:71], s[10:11], v70, s82, v[36:37]
	v_mad_u64_u32 v[72:73], s[10:11], v72, s82, v[36:37]
	v_mad_u64_u32 v[74:75], s[10:11], v74, s82, v[36:37]
	global_load_dword v35, v[44:45], off nt
	global_load_dword v38, v[46:47], off nt
	global_load_dword v76, v[48:49], off nt
	global_load_dword v77, v[50:51], off nt
	global_load_dword v78, v[52:53], off nt
	global_load_dword v79, v[54:55], off nt
	global_load_dword v80, v[56:57], off nt
	global_load_dword v81, v[58:59], off nt
	global_load_dword v82, v[60:61], off nt
	global_load_dword v83, v[62:63], off nt
	global_load_dword v84, v[64:65], off nt
	global_load_dword v85, v[66:67], off nt
	global_load_dword v86, v[68:69], off nt
	global_load_dword v87, v[70:71], off nt
	global_load_dword v88, v[72:73], off nt
	global_load_dword v89, v[74:75], off nt
	v_or_b32_e32 v46, s34, v3
	v_or_b32_e32 v44, s35, v2
	s_add_i32 s21, s21, 16
	s_add_i32 s20, s20, 16
	s_add_i32 s31, s31, -16
	v_mad_u64_u32 v[44:45], s[10:11], v44, s27, v[6:7]
	v_mad_u64_u32 v[46:47], s[10:11], v46, s27, v[6:7]
	v_or_b32_e32 v45, s36, v3
	v_or_b32_e32 v47, s37, v2
	v_or_b32_e32 v54, s38, v3
	v_or_b32_e32 v52, s39, v2
	v_or_b32_e32 v58, s40, v3
	v_or_b32_e32 v56, s41, v2
	v_or_b32_e32 v62, s42, v3
	v_or_b32_e32 v60, s43, v2
	v_or_b32_e32 v66, s44, v3
	v_or_b32_e32 v64, s45, v2
	v_or_b32_e32 v70, s46, v3
	v_or_b32_e32 v68, s47, v2
	v_or_b32_e32 v74, s48, v3
	v_or_b32_e32 v72, s49, v2
	s_cmp_lg_u32 s31, 0
	v_mad_u64_u32 v[48:49], s[10:11], v47, s27, v[6:7]
	v_mad_u64_u32 v[50:51], s[10:11], v45, s27, v[6:7]
	v_mad_u64_u32 v[52:53], s[10:11], v52, s27, v[6:7]
	v_mad_u64_u32 v[54:55], s[10:11], v54, s27, v[6:7]
	v_mad_u64_u32 v[56:57], s[10:11], v56, s27, v[6:7]
	v_mad_u64_u32 v[58:59], s[10:11], v58, s27, v[6:7]
	v_mad_u64_u32 v[60:61], s[10:11], v60, s27, v[6:7]
	v_mad_u64_u32 v[62:63], s[10:11], v62, s27, v[6:7]
	v_mad_u64_u32 v[64:65], s[10:11], v64, s27, v[6:7]
	v_mad_u64_u32 v[66:67], s[10:11], v66, s27, v[6:7]
	v_mad_u64_u32 v[68:69], s[10:11], v68, s27, v[6:7]
	v_mad_u64_u32 v[70:71], s[10:11], v70, s27, v[6:7]
	v_mad_u64_u32 v[72:73], s[10:11], v72, s27, v[6:7]
	v_mad_u64_u32 v[74:75], s[10:11], v74, s27, v[6:7]
	s_waitcnt vmcnt(15)
	ds_write_b32 v44, v35
	s_waitcnt vmcnt(14)
	ds_write_b32 v46, v38
	s_waitcnt vmcnt(13)
	ds_write_b32 v48, v76
	s_waitcnt vmcnt(12)
	ds_write_b32 v50, v77
	s_waitcnt vmcnt(11)
	ds_write_b32 v52, v78
	s_waitcnt vmcnt(10)
	ds_write_b32 v54, v79
	s_waitcnt vmcnt(9)
	ds_write_b32 v56, v80
	s_waitcnt vmcnt(8)
	ds_write_b32 v58, v81
	s_waitcnt vmcnt(7)
	ds_write_b32 v60, v82
	s_waitcnt vmcnt(6)
	ds_write_b32 v62, v83
	s_waitcnt vmcnt(5)
	ds_write_b32 v64, v84
	s_waitcnt vmcnt(4)
	ds_write_b32 v66, v85
	s_waitcnt vmcnt(3)
	ds_write_b32 v68, v86
	s_waitcnt vmcnt(2)
	ds_write_b32 v70, v87
	s_waitcnt vmcnt(1)
	ds_write_b32 v72, v88
	s_waitcnt vmcnt(0)
	ds_write_b32 v74, v89
	s_cbranch_scc1 .LBB0_61
; #define LAS __attribute__((address_space(3)))
; __device__ __forceinline__ unsigned pk2(float lo, float hi) { return f2bf(lo) | (f2bf(hi) << 16); }
; __device__ __forceinline__ void tr_item(const float* W, int ldw, int c0, bf16* WT, int ldk, int r0, int nblk, int item, LAS float* scr, int lane) {
;     ...
;     asm volatile("s_waitcnt lgkmcnt(0)" ::: "memory");
;     const int c = lane & 7;
; #pragma unroll
;     for (int j = 0; j < 4; ++j) { const int n = (lane >> 3) + 8 * j; const LAS float* s = scr + (8 * c) * 33 + n;
;         v4u o; o.x = pk2(s[0 * 33], s[1 * 33]); o.y = pk2(s[2 * 33], s[3 * 33]); o.z = pk2(s[4 * 33], s[5 * 33]); o.w = pk2(s[6 * 33], s[7 * 33]);
;         *(v4u*)(WT + (size_t)(r0 + n0 + n) * ldk + k0 + 8 * c) = o; }
;     asm volatile("s_waitcnt lgkmcnt(0)" ::: "memory");
	s_waitcnt lgkmcnt(0)
	ds_read2_b32 v[36:37], v40 offset1:8
	ds_read2_b32 v[50:51], v40 offset0:33 offset1:41
	ds_read2_b32 v[52:53], v40 offset0:66 offset1:74
	ds_read2_b32 v[54:55], v40 offset0:99 offset1:107
	ds_read2_b32 v[56:57], v40 offset0:132 offset1:140
	s_mov_b32 s85, 0xffff0000
	s_waitcnt lgkmcnt(4)
	v_bfe_u32 v0, v36, 16, 1
	v_add3_u32 v0, v36, v0, s80
	s_waitcnt lgkmcnt(3)
	v_bfe_u32 v7, v50, 16, 1
	v_lshrrev_b32_e32 v0, 16, v0
	v_add3_u32 v7, v50, v7, s80
	ds_read2_b32 v[58:59], v40 offset0:165 offset1:173
	v_and_or_b32 v44, v7, s85, v0
	s_waitcnt lgkmcnt(3)
	v_bfe_u32 v0, v52, 16, 1
	v_add3_u32 v0, v52, v0, s80
	s_waitcnt lgkmcnt(2)
	v_bfe_u32 v7, v54, 16, 1
	ds_read2_b32 v[60:61], v40 offset0:198 offset1:206
	v_lshrrev_b32_e32 v0, 16, v0
	v_add3_u32 v7, v54, v7, s80
	ds_read2_b32 v[62:63], v40 offset0:231 offset1:239
	v_and_or_b32 v45, v7, s85, v0
	s_waitcnt lgkmcnt(3)
	v_bfe_u32 v0, v56, 16, 1
	v_add3_u32 v0, v56, v0, s80
	s_waitcnt lgkmcnt(2)
	v_bfe_u32 v7, v58, 16, 1
	v_lshrrev_b32_e32 v0, 16, v0
	v_add3_u32 v7, v58, v7, s80
	v_and_or_b32 v46, v7, s85, v0
	s_waitcnt lgkmcnt(1)
	v_bfe_u32 v0, v60, 16, 1
	v_add3_u32 v0, v60, v0, s80
	s_waitcnt lgkmcnt(0)
	v_bfe_u32 v7, v62, 16, 1
	v_lshrrev_b32_e32 v0, 16, v0
	v_add3_u32 v7, v62, v7, s80
	s_lshl_b32 s88, s4, 1
	v_and_or_b32 v47, v7, s85, v0
	v_or_b32_e32 v0, s1, v39
	v_lshl_add_u64 v[48:49], v[22:23], 0, s[88:89]
	v_lshlrev_b32_e32 v0, 9, v0
	v_lshl_add_u64 v[64:65], v[48:49], 0, v[0:1]
	v_bfe_u32 v0, v37, 16, 1
	v_add3_u32 v0, v37, v0, s80
	v_bfe_u32 v7, v51, 16, 1
	v_lshrrev_b32_e32 v0, 16, v0
	v_add3_u32 v7, v51, v7, s80
	global_store_dwordx4 v[64:65], v[44:47], off
	ds_read2_b32 v[36:37], v40 offset0:16 offset1:24
	v_readlane_b32 s81, v254, 55
	v_and_or_b32 v44, v7, s85, v0
	v_bfe_u32 v0, v53, 16, 1
	v_add3_u32 v0, v53, v0, s80
	v_bfe_u32 v7, v55, 16, 1
	v_lshrrev_b32_e32 v0, 16, v0
	v_add3_u32 v7, v55, v7, s80
	v_and_or_b32 v45, v7, s85, v0
	v_bfe_u32 v0, v57, 16, 1
	v_add3_u32 v0, v57, v0, s80
	v_bfe_u32 v7, v59, 16, 1
	v_lshrrev_b32_e32 v0, 16, v0
	v_add3_u32 v7, v59, v7, s80
	v_and_or_b32 v46, v7, s85, v0
	v_bfe_u32 v0, v61, 16, 1
	v_add3_u32 v0, v61, v0, s80
	v_bfe_u32 v7, v63, 16, 1
	v_lshrrev_b32_e32 v0, 16, v0
	v_add3_u32 v7, v63, v7, s80
	v_and_or_b32 v47, v7, s85, v0
	v_or_b32_e32 v0, s1, v41
	v_lshlrev_b32_e32 v0, 9, v0
	v_lshl_add_u64 v[50:51], v[48:49], 0, v[0:1]
	global_store_dwordx4 v[50:51], v[44:47], off
	ds_read2_b32 v[50:51], v40 offset0:49 offset1:57
	ds_read2_b32 v[52:53], v40 offset0:82 offset1:90
	ds_read2_b32 v[54:55], v40 offset0:115 offset1:123
	s_waitcnt lgkmcnt(3)
	v_bfe_u32 v0, v36, 16, 1
	v_add3_u32 v0, v36, v0, s80
	s_waitcnt lgkmcnt(2)
	v_bfe_u32 v7, v50, 16, 1
	ds_read2_b32 v[56:57], v40 offset0:148 offset1:156
	v_lshrrev_b32_e32 v0, 16, v0
	v_add3_u32 v7, v50, v7, s80
	ds_read2_b32 v[58:59], v40 offset0:181 offset1:189
	v_and_or_b32 v44, v7, s85, v0
	s_waitcnt lgkmcnt(3)
	v_bfe_u32 v0, v52, 16, 1
	v_add3_u32 v0, v52, v0, s80
	s_waitcnt lgkmcnt(2)
	v_bfe_u32 v7, v54, 16, 1
	ds_read2_b32 v[60:61], v40 offset0:214 offset1:222
	v_lshrrev_b32_e32 v0, 16, v0
	v_add3_u32 v7, v54, v7, s80
	ds_read2_b32 v[62:63], v40 offset0:247 offset1:255
	v_and_or_b32 v45, v7, s85, v0
	s_waitcnt lgkmcnt(3)
	v_bfe_u32 v0, v56, 16, 1
	v_add3_u32 v0, v56, v0, s80
	s_waitcnt lgkmcnt(2)
	v_bfe_u32 v7, v58, 16, 1
	v_lshrrev_b32_e32 v0, 16, v0
	v_add3_u32 v7, v58, v7, s80
	v_and_or_b32 v46, v7, s85, v0
	s_waitcnt lgkmcnt(1)
	v_bfe_u32 v0, v60, 16, 1
	v_add3_u32 v0, v60, v0, s80
	s_waitcnt lgkmcnt(0)
	v_bfe_u32 v7, v62, 16, 1
	v_lshrrev_b32_e32 v0, 16, v0
	v_add3_u32 v7, v62, v7, s80
	v_and_or_b32 v47, v7, s85, v0
	v_or_b32_e32 v0, s1, v42
	v_lshlrev_b32_e32 v0, 9, v0
	v_lshl_add_u64 v[64:65], v[48:49], 0, v[0:1]
	v_bfe_u32 v0, v37, 16, 1
	v_add3_u32 v0, v37, v0, s80
	v_bfe_u32 v7, v51, 16, 1
	v_lshrrev_b32_e32 v0, 16, v0
	v_add3_u32 v7, v51, v7, s80
	global_store_dwordx4 v[64:65], v[44:47], off
	s_nop 1
	v_and_or_b32 v44, v7, s85, v0
	v_bfe_u32 v0, v53, 16, 1
	v_add3_u32 v0, v53, v0, s80
	v_bfe_u32 v7, v55, 16, 1
	v_lshrrev_b32_e32 v0, 16, v0
	v_add3_u32 v7, v55, v7, s80
	v_and_or_b32 v45, v7, s85, v0
	v_bfe_u32 v0, v57, 16, 1
	v_add3_u32 v0, v57, v0, s80
	v_bfe_u32 v7, v59, 16, 1
	v_lshrrev_b32_e32 v0, 16, v0
	v_add3_u32 v7, v59, v7, s80
	v_and_or_b32 v46, v7, s85, v0
	v_bfe_u32 v0, v61, 16, 1
	v_add3_u32 v0, v61, v0, s80
	v_bfe_u32 v7, v63, 16, 1
	v_lshrrev_b32_e32 v0, 16, v0
	v_add3_u32 v7, v63, v7, s80
	v_and_or_b32 v47, v7, s85, v0
	v_or_b32_e32 v0, s1, v43
	v_lshlrev_b32_e32 v0, 9, v0
	v_lshl_add_u64 v[36:37], v[48:49], 0, v[0:1]
	global_store_dwordx4 v[36:37], v[44:47], off
	s_waitcnt lgkmcnt(0)

; #define LAS __attribute__((address_space(3)))
; __device__ __forceinline__ void tr_item(const float* W, int ldw, int c0, bf16* WT, int ldk, int r0, int nblk, int item, LAS float* scr, int lane) {
;     const int kb = item / nblk, nb = item % nblk, k0 = 64 * kb, n0 = 32 * nb;
; #pragma unroll 8
;     for (int i = 0; i < 32; ++i) { const int kk = 2 * i + (lane >> 5); scr[kk * 33 + (lane & 31)] = W[(size_t)(k0 + kk) * ldw + c0 + n0 + (lane & 31)]; }
.LBB0_66:
	s_lshl_b32 s34, s20, 1
	s_lshl_b32 s35, s21, 1
	v_or_b32_e32 v35, s34, v7
	v_or_b32_e32 v38, s35, v0
	s_add_i32 s36, s34, 4
	s_add_i32 s37, s35, 4
	s_add_i32 s38, s34, 8
	s_add_i32 s39, s35, 8
	s_add_i32 s40, s34, 12
	s_add_i32 s41, s35, 12
	s_add_i32 s42, s34, 16
	s_add_i32 s43, s35, 16
	s_add_i32 s44, s34, 20
	s_add_i32 s45, s35, 20
	s_add_i32 s46, s34, 24
	s_add_i32 s47, s35, 24
	s_add_i32 s48, s34, 28
	s_add_i32 s49, s35, 28
	v_mad_u64_u32 v[44:45], s[10:11], v38, s83, v[36:37]
	v_mad_u64_u32 v[46:47], s[10:11], v35, s83, v[36:37]
	v_or_b32_e32 v35, s36, v7
	v_or_b32_e32 v38, s37, v0
	v_or_b32_e32 v54, s38, v7
	v_or_b32_e32 v52, s39, v0
	v_or_b32_e32 v58, s40, v7
	v_or_b32_e32 v56, s41, v0
	v_or_b32_e32 v62, s42, v7
	v_or_b32_e32 v60, s43, v0
	v_or_b32_e32 v66, s44, v7
	v_or_b32_e32 v64, s45, v0
	v_or_b32_e32 v70, s46, v7
	v_or_b32_e32 v68, s47, v0
	v_or_b32_e32 v74, s48, v7
	v_or_b32_e32 v72, s49, v0
	v_mad_u64_u32 v[48:49], s[10:11], v38, s83, v[36:37]
	v_mad_u64_u32 v[50:51], s[10:11], v35, s83, v[36:37]
	v_mad_u64_u32 v[52:53], s[10:11], v52, s83, v[36:37]
	v_mad_u64_u32 v[54:55], s[10:11], v54, s83, v[36:37]
	v_mad_u64_u32 v[56:57], s[10:11], v56, s83, v[36:37]
	v_mad_u64_u32 v[58:59], s[10:11], v58, s83, v[36:37]
	v_mad_u64_u32 v[60:61], s[10:11], v60, s83, v[36:37]
	v_mad_u64_u32 v[62:63], s[10:11], v62, s83, v[36:37]
	v_mad_u64_u32 v[64:65], s[10:11], v64, s83, v[36:37]
	v_mad_u64_u32 v[66:67], s[10:11], v66, s83, v[36:37]
	v_mad_u64_u32 v[68:69], s[10:11], v68, s83, v[36:37]
	v_mad_u64_u32 v[70:71], s[10:11], v70, s83, v[36:37]
	v_mad_u64_u32 v[72:73], s[10:11], v72, s83, v[36:37]
	v_mad_u64_u32 v[74:75], s[10:11], v74, s83, v[36:37]
	global_load_dword v35, v[44:45], off nt
	global_load_dword v38, v[46:47], off nt
	global_load_dword v76, v[48:49], off nt
	global_load_dword v77, v[50:51], off nt
	global_load_dword v78, v[52:53], off nt
	global_load_dword v79, v[54:55], off nt
	global_load_dword v80, v[56:57], off nt
	global_load_dword v81, v[58:59], off nt
	global_load_dword v82, v[60:61], off nt
	global_load_dword v83, v[62:63], off nt
	global_load_dword v84, v[64:65], off nt
	global_load_dword v85, v[66:67], off nt
	global_load_dword v86, v[68:69], off nt
	global_load_dword v87, v[70:71], off nt
	global_load_dword v88, v[72:73], off nt
	global_load_dword v89, v[74:75], off nt
	v_or_b32_e32 v46, s34, v3
	v_or_b32_e32 v44, s35, v2
	s_add_i32 s21, s21, 16
	s_add_i32 s20, s20, 16
	s_add_i32 s31, s31, -16
	v_mad_u64_u32 v[44:45], s[10:11], v44, s27, v[6:7]
	v_mad_u64_u32 v[46:47], s[10:11], v46, s27, v[6:7]
	v_or_b32_e32 v45, s36, v3
	v_or_b32_e32 v47, s37, v2
	v_or_b32_e32 v54, s38, v3
	v_or_b32_e32 v52, s39, v2
	v_or_b32_e32 v58, s40, v3
	v_or_b32_e32 v56, s41, v2
	v_or_b32_e32 v62, s42, v3
	v_or_b32_e32 v60, s43, v2
	v_or_b32_e32 v66, s44, v3
	v_or_b32_e32 v64, s45, v2
	v_or_b32_e32 v70, s46, v3
	v_or_b32_e32 v68, s47, v2
	v_or_b32_e32 v74, s48, v3
	v_or_b32_e32 v72, s49, v2
	s_cmp_lg_u32 s31, 0
	v_mad_u64_u32 v[48:49], s[10:11], v47, s27, v[6:7]
	v_mad_u64_u32 v[50:51], s[10:11], v45, s27, v[6:7]
	v_mad_u64_u32 v[52:53], s[10:11], v52, s27, v[6:7]
	v_mad_u64_u32 v[54:55], s[10:11], v54, s27, v[6:7]
	v_mad_u64_u32 v[56:57], s[10:11], v56, s27, v[6:7]
	v_mad_u64_u32 v[58:59], s[10:11], v58, s27, v[6:7]
	v_mad_u64_u32 v[60:61], s[10:11], v60, s27, v[6:7]
	v_mad_u64_u32 v[62:63], s[10:11], v62, s27, v[6:7]
	v_mad_u64_u32 v[64:65], s[10:11], v64, s27, v[6:7]
	v_mad_u64_u32 v[66:67], s[10:11], v66, s27, v[6:7]
	v_mad_u64_u32 v[68:69], s[10:11], v68, s27, v[6:7]
	v_mad_u64_u32 v[70:71], s[10:11], v70, s27, v[6:7]
	v_mad_u64_u32 v[72:73], s[10:11], v72, s27, v[6:7]
	v_mad_u64_u32 v[74:75], s[10:11], v74, s27, v[6:7]
	s_waitcnt vmcnt(15)
	ds_write_b32 v44, v35
	s_waitcnt vmcnt(14)
	ds_write_b32 v46, v38
	s_waitcnt vmcnt(13)
	ds_write_b32 v48, v76
	s_waitcnt vmcnt(12)
	ds_write_b32 v50, v77
	s_waitcnt vmcnt(11)
	ds_write_b32 v52, v78
	s_waitcnt vmcnt(10)
	ds_write_b32 v54, v79
	s_waitcnt vmcnt(9)
	ds_write_b32 v56, v80
	s_waitcnt vmcnt(8)
	ds_write_b32 v58, v81
	s_waitcnt vmcnt(7)
	ds_write_b32 v60, v82
	s_waitcnt vmcnt(6)
	ds_write_b32 v62, v83
	s_waitcnt vmcnt(5)
	ds_write_b32 v64, v84
	s_waitcnt vmcnt(4)
	ds_write_b32 v66, v85
	s_waitcnt vmcnt(3)
	ds_write_b32 v68, v86
	s_waitcnt vmcnt(2)
	ds_write_b32 v70, v87
	s_waitcnt vmcnt(1)
	ds_write_b32 v72, v88
	s_waitcnt vmcnt(0)
	ds_write_b32 v74, v89
	s_cbranch_scc1 .LBB0_66
; #define LAS __attribute__((address_space(3)))
; __device__ __forceinline__ unsigned pk2(float lo, float hi) { return f2bf(lo) | (f2bf(hi) << 16); }
; __device__ __forceinline__ void tr_item(const float* W, int ldw, int c0, bf16* WT, int ldk, int r0, int nblk, int item, LAS float* scr, int lane) {
;     ...
;     asm volatile("s_waitcnt lgkmcnt(0)" ::: "memory");
;     const int c = lane & 7;
; #pragma unroll
;     for (int j = 0; j < 4; ++j) { const int n = (lane >> 3) + 8 * j; const LAS float* s = scr + (8 * c) * 33 + n;
;         v4u o; o.x = pk2(s[0 * 33], s[1 * 33]); o.y = pk2(s[2 * 33], s[3 * 33]); o.z = pk2(s[4 * 33], s[5 * 33]); o.w = pk2(s[6 * 33], s[7 * 33]);
;         *(v4u*)(WT + (size_t)(r0 + n0 + n) * ldk + k0 + 8 * c) = o; }
;     asm volatile("s_waitcnt lgkmcnt(0)" ::: "memory");
	s_waitcnt lgkmcnt(0)
	ds_read2_b32 v[36:37], v40 offset1:8
	ds_read2_b32 v[50:51], v40 offset0:33 offset1:41
	ds_read2_b32 v[52:53], v40 offset0:66 offset1:74
	ds_read2_b32 v[54:55], v40 offset0:99 offset1:107
	ds_read2_b32 v[56:57], v40 offset0:132 offset1:140
	s_waitcnt lgkmcnt(4)
	v_bfe_u32 v0, v36, 16, 1
	v_add3_u32 v0, v36, v0, s80
	s_waitcnt lgkmcnt(3)
	v_bfe_u32 v7, v50, 16, 1
	v_lshrrev_b32_e32 v0, 16, v0
	v_add3_u32 v7, v50, v7, s80
	s_mov_b32 s85, 0xffff0000
	ds_read2_b32 v[58:59], v40 offset0:165 offset1:173
	v_and_or_b32 v44, v7, s85, v0
	s_waitcnt lgkmcnt(3)
	v_bfe_u32 v0, v52, 16, 1
	v_add3_u32 v0, v52, v0, s80
	s_waitcnt lgkmcnt(2)
	v_bfe_u32 v7, v54, 16, 1
	ds_read2_b32 v[60:61], v40 offset0:198 offset1:206
	v_lshrrev_b32_e32 v0, 16, v0
	v_add3_u32 v7, v54, v7, s80
	ds_read2_b32 v[62:63], v40 offset0:231 offset1:239
	v_and_or_b32 v45, v7, s85, v0
	s_waitcnt lgkmcnt(3)
	v_bfe_u32 v0, v56, 16, 1
	v_add3_u32 v0, v56, v0, s80
	s_waitcnt lgkmcnt(2)
	v_bfe_u32 v7, v58, 16, 1
	v_lshrrev_b32_e32 v0, 16, v0
	v_add3_u32 v7, v58, v7, s80
	v_and_or_b32 v46, v7, s85, v0
	s_waitcnt lgkmcnt(1)
	v_bfe_u32 v0, v60, 16, 1
	v_add3_u32 v0, v60, v0, s80
	s_waitcnt lgkmcnt(0)
	v_bfe_u32 v7, v62, 16, 1
	s_and_b32 s4, 0xffff, s4
	s_and_b32 s1, 0xffff, s1
	v_lshrrev_b32_e32 v0, 16, v0
	v_add3_u32 v7, v62, v7, s80
	s_lshl_b32 s88, s1, 1
	v_and_or_b32 v47, v7, s85, v0
	v_or_b32_e32 v0, s4, v39
	v_lshl_add_u64 v[48:49], v[28:29], 0, s[88:89]
	v_lshlrev_b32_e32 v0, 11, v0
	v_lshl_add_u64 v[64:65], v[48:49], 0, v[0:1]
	v_bfe_u32 v0, v37, 16, 1
	v_add3_u32 v0, v37, v0, s80
	v_bfe_u32 v7, v51, 16, 1
	v_lshrrev_b32_e32 v0, 16, v0
	v_add3_u32 v7, v51, v7, s80
	global_store_dwordx4 v[64:65], v[44:47], off
	ds_read2_b32 v[36:37], v40 offset0:16 offset1:24
	v_readlane_b32 s81, v254, 55
	v_and_or_b32 v44, v7, s85, v0
	v_bfe_u32 v0, v53, 16, 1
	v_add3_u32 v0, v53, v0, s80
	v_bfe_u32 v7, v55, 16, 1
	v_lshrrev_b32_e32 v0, 16, v0
	v_add3_u32 v7, v55, v7, s80
	v_and_or_b32 v45, v7, s85, v0
	v_bfe_u32 v0, v57, 16, 1
	v_add3_u32 v0, v57, v0, s80
	v_bfe_u32 v7, v59, 16, 1
	v_lshrrev_b32_e32 v0, 16, v0
	v_add3_u32 v7, v59, v7, s80
	v_and_or_b32 v46, v7, s85, v0
	v_bfe_u32 v0, v61, 16, 1
	v_add3_u32 v0, v61, v0, s80
	v_bfe_u32 v7, v63, 16, 1
	v_lshrrev_b32_e32 v0, 16, v0
	v_add3_u32 v7, v63, v7, s80
	v_and_or_b32 v47, v7, s85, v0
	v_or_b32_e32 v0, s4, v41
	v_lshlrev_b32_e32 v0, 11, v0
	v_lshl_add_u64 v[50:51], v[48:49], 0, v[0:1]
	global_store_dwordx4 v[50:51], v[44:47], off
	ds_read2_b32 v[50:51], v40 offset0:49 offset1:57
	ds_read2_b32 v[52:53], v40 offset0:82 offset1:90
	ds_read2_b32 v[54:55], v40 offset0:115 offset1:123
	s_waitcnt lgkmcnt(3)
	v_bfe_u32 v0, v36, 16, 1
	v_add3_u32 v0, v36, v0, s80
	s_waitcnt lgkmcnt(2)
	v_bfe_u32 v7, v50, 16, 1
	ds_read2_b32 v[56:57], v40 offset0:148 offset1:156
	v_lshrrev_b32_e32 v0, 16, v0
	v_add3_u32 v7, v50, v7, s80
	ds_read2_b32 v[58:59], v40 offset0:181 offset1:189
	v_and_or_b32 v44, v7, s85, v0
	s_waitcnt lgkmcnt(3)
	v_bfe_u32 v0, v52, 16, 1
	v_add3_u32 v0, v52, v0, s80
	s_waitcnt lgkmcnt(2)
	v_bfe_u32 v7, v54, 16, 1
	ds_read2_b32 v[60:61], v40 offset0:214 offset1:222
	v_lshrrev_b32_e32 v0, 16, v0
	v_add3_u32 v7, v54, v7, s80
	ds_read2_b32 v[62:63], v40 offset0:247 offset1:255
	v_and_or_b32 v45, v7, s85, v0
	s_waitcnt lgkmcnt(3)
	v_bfe_u32 v0, v56, 16, 1
	v_add3_u32 v0, v56, v0, s80
	s_waitcnt lgkmcnt(2)
	v_bfe_u32 v7, v58, 16, 1
	v_lshrrev_b32_e32 v0, 16, v0
	v_add3_u32 v7, v58, v7, s80
	v_and_or_b32 v46, v7, s85, v0
	s_waitcnt lgkmcnt(1)
	v_bfe_u32 v0, v60, 16, 1
	v_add3_u32 v0, v60, v0, s80
	s_waitcnt lgkmcnt(0)
	v_bfe_u32 v7, v62, 16, 1
	v_lshrrev_b32_e32 v0, 16, v0
	v_add3_u32 v7, v62, v7, s80
	v_and_or_b32 v47, v7, s85, v0
	v_or_b32_e32 v0, s4, v42
	v_lshlrev_b32_e32 v0, 11, v0
	v_lshl_add_u64 v[64:65], v[48:49], 0, v[0:1]
	v_bfe_u32 v0, v37, 16, 1
	v_add3_u32 v0, v37, v0, s80
	v_bfe_u32 v7, v51, 16, 1
	v_lshrrev_b32_e32 v0, 16, v0
	v_add3_u32 v7, v51, v7, s80
	global_store_dwordx4 v[64:65], v[44:47], off
	s_nop 1
	v_and_or_b32 v44, v7, s85, v0
	v_bfe_u32 v0, v53, 16, 1
	v_add3_u32 v0, v53, v0, s80
	v_bfe_u32 v7, v55, 16, 1
	v_lshrrev_b32_e32 v0, 16, v0
	v_add3_u32 v7, v55, v7, s80
	v_and_or_b32 v45, v7, s85, v0
	v_bfe_u32 v0, v57, 16, 1
	v_add3_u32 v0, v57, v0, s80
	v_bfe_u32 v7, v59, 16, 1
	v_lshrrev_b32_e32 v0, 16, v0
	v_add3_u32 v7, v59, v7, s80
	v_and_or_b32 v46, v7, s85, v0
	v_bfe_u32 v0, v61, 16, 1
	v_add3_u32 v0, v61, v0, s80
	v_bfe_u32 v7, v63, 16, 1
	v_lshrrev_b32_e32 v0, 16, v0
	v_add3_u32 v7, v63, v7, s80
	v_and_or_b32 v47, v7, s85, v0
	v_or_b32_e32 v0, s4, v43
	v_lshlrev_b32_e32 v0, 11, v0
	v_lshl_add_u64 v[36:37], v[48:49], 0, v[0:1]
	global_store_dwordx4 v[36:37], v[44:47], off
	s_waitcnt lgkmcnt(0)

; #define LAS __attribute__((address_space(3)))
; __device__ __forceinline__ void tr_item(const float* W, int ldw, int c0, bf16* WT, int ldk, int r0, int nblk, int item, LAS float* scr, int lane) {
;     const int kb = item / nblk, nb = item % nblk, k0 = 64 * kb, n0 = 32 * nb;
; #pragma unroll 8
;     for (int i = 0; i < 32; ++i) { const int kk = 2 * i + (lane >> 5); scr[kk * 33 + (lane & 31)] = W[(size_t)(k0 + kk) * ldw + c0 + n0 + (lane & 31)]; }
.LBB0_71:
	s_lshl_b32 s31, s1, 1
	s_lshl_b32 s34, s4, 1
	v_or_b32_e32 v35, s31, v7
	v_or_b32_e32 v38, s34, v0
	s_add_i32 s35, s31, 4
	s_add_i32 s37, s34, 4
	s_add_i32 s38, s31, 8
	s_add_i32 s39, s34, 8
	s_add_i32 s40, s31, 12
	s_add_i32 s41, s34, 12
	s_add_i32 s42, s31, 16
	s_add_i32 s43, s34, 16
	s_add_i32 s44, s31, 20
	s_add_i32 s45, s34, 20
	s_add_i32 s46, s31, 24
	s_add_i32 s47, s34, 24
	s_add_i32 s48, s31, 28
	s_add_i32 s49, s34, 28
	v_mad_i64_i32 v[44:45], s[10:11], v38, s83, v[36:37]
	v_mad_i64_i32 v[46:47], s[10:11], v35, s83, v[36:37]
	v_or_b32_e32 v35, s35, v7
	v_or_b32_e32 v38, s37, v0
	v_or_b32_e32 v54, s38, v7
	v_or_b32_e32 v52, s39, v0
	v_or_b32_e32 v58, s40, v7
	v_or_b32_e32 v56, s41, v0
	v_or_b32_e32 v62, s42, v7
	v_or_b32_e32 v60, s43, v0
	v_or_b32_e32 v66, s44, v7
	v_or_b32_e32 v64, s45, v0
	v_or_b32_e32 v70, s46, v7
	v_or_b32_e32 v68, s47, v0
	v_or_b32_e32 v74, s48, v7
	v_or_b32_e32 v72, s49, v0
	v_mad_i64_i32 v[48:49], s[10:11], v38, s83, v[36:37]
	v_mad_i64_i32 v[50:51], s[10:11], v35, s83, v[36:37]
	v_mad_i64_i32 v[52:53], s[10:11], v52, s83, v[36:37]
	v_mad_i64_i32 v[54:55], s[10:11], v54, s83, v[36:37]
	v_mad_i64_i32 v[56:57], s[10:11], v56, s83, v[36:37]
	v_mad_i64_i32 v[58:59], s[10:11], v58, s83, v[36:37]
	v_mad_i64_i32 v[60:61], s[10:11], v60, s83, v[36:37]
	v_mad_i64_i32 v[62:63], s[10:11], v62, s83, v[36:37]
	v_mad_i64_i32 v[64:65], s[10:11], v64, s83, v[36:37]
	v_mad_i64_i32 v[66:67], s[10:11], v66, s83, v[36:37]
	v_mad_i64_i32 v[68:69], s[10:11], v68, s83, v[36:37]
	v_mad_i64_i32 v[70:71], s[10:11], v70, s83, v[36:37]
	v_mad_i64_i32 v[72:73], s[10:11], v72, s83, v[36:37]
	v_mad_i64_i32 v[74:75], s[10:11], v74, s83, v[36:37]
	global_load_dword v35, v[44:45], off nt
	global_load_dword v38, v[46:47], off nt
	global_load_dword v76, v[48:49], off nt
	global_load_dword v77, v[50:51], off nt
	global_load_dword v78, v[52:53], off nt
	global_load_dword v79, v[54:55], off nt
	global_load_dword v80, v[56:57], off nt
	global_load_dword v81, v[58:59], off nt
	global_load_dword v82, v[60:61], off nt
	global_load_dword v83, v[62:63], off nt
	global_load_dword v84, v[64:65], off nt
	global_load_dword v85, v[66:67], off nt
	global_load_dword v86, v[68:69], off nt
	global_load_dword v87, v[70:71], off nt
	global_load_dword v88, v[72:73], off nt
	global_load_dword v89, v[74:75], off nt
	v_or_b32_e32 v46, s31, v3
	v_or_b32_e32 v44, s34, v2
	s_add_i32 s4, s4, 16
	s_add_i32 s1, s1, 16
	s_add_i32 s21, s21, -16
	v_mad_u64_u32 v[44:45], s[10:11], v44, s27, v[6:7]
	v_mad_u64_u32 v[46:47], s[10:11], v46, s27, v[6:7]
	v_or_b32_e32 v45, s35, v3
	v_or_b32_e32 v47, s37, v2
	v_or_b32_e32 v54, s38, v3
	v_or_b32_e32 v52, s39, v2
	v_or_b32_e32 v58, s40, v3
	v_or_b32_e32 v56, s41, v2
	v_or_b32_e32 v62, s42, v3
	v_or_b32_e32 v60, s43, v2
	v_or_b32_e32 v66, s44, v3
	v_or_b32_e32 v64, s45, v2
	v_or_b32_e32 v70, s46, v3
	v_or_b32_e32 v68, s47, v2
	v_or_b32_e32 v74, s48, v3
	v_or_b32_e32 v72, s49, v2
	s_cmp_lg_u32 s21, 0
	v_mad_u64_u32 v[48:49], s[10:11], v47, s27, v[6:7]
	v_mad_u64_u32 v[50:51], s[10:11], v45, s27, v[6:7]
	v_mad_u64_u32 v[52:53], s[10:11], v52, s27, v[6:7]
	v_mad_u64_u32 v[54:55], s[10:11], v54, s27, v[6:7]
	v_mad_u64_u32 v[56:57], s[10:11], v56, s27, v[6:7]
	v_mad_u64_u32 v[58:59], s[10:11], v58, s27, v[6:7]
	v_mad_u64_u32 v[60:61], s[10:11], v60, s27, v[6:7]
	v_mad_u64_u32 v[62:63], s[10:11], v62, s27, v[6:7]
	v_mad_u64_u32 v[64:65], s[10:11], v64, s27, v[6:7]
	v_mad_u64_u32 v[66:67], s[10:11], v66, s27, v[6:7]
	v_mad_u64_u32 v[68:69], s[10:11], v68, s27, v[6:7]
	v_mad_u64_u32 v[70:71], s[10:11], v70, s27, v[6:7]
	v_mad_u64_u32 v[72:73], s[10:11], v72, s27, v[6:7]
	v_mad_u64_u32 v[74:75], s[10:11], v74, s27, v[6:7]
	s_waitcnt vmcnt(15)
	ds_write_b32 v44, v35
	s_waitcnt vmcnt(14)
	ds_write_b32 v46, v38
	s_waitcnt vmcnt(13)
	ds_write_b32 v48, v76
	s_waitcnt vmcnt(12)
	ds_write_b32 v50, v77
	s_waitcnt vmcnt(11)
	ds_write_b32 v52, v78
	s_waitcnt vmcnt(10)
	ds_write_b32 v54, v79
	s_waitcnt vmcnt(9)
	ds_write_b32 v56, v80
	s_waitcnt vmcnt(8)
	ds_write_b32 v58, v81
	s_waitcnt vmcnt(7)
	ds_write_b32 v60, v82
	s_waitcnt vmcnt(6)
	ds_write_b32 v62, v83
	s_waitcnt vmcnt(5)
	ds_write_b32 v64, v84
	s_waitcnt vmcnt(4)
	ds_write_b32 v66, v85
	s_waitcnt vmcnt(3)
	ds_write_b32 v68, v86
	s_waitcnt vmcnt(2)
	ds_write_b32 v70, v87
	s_waitcnt vmcnt(1)
	ds_write_b32 v72, v88
	s_waitcnt vmcnt(0)
	ds_write_b32 v74, v89
	s_cbranch_scc1 .LBB0_71
; #define LAS __attribute__((address_space(3)))
; __device__ __forceinline__ unsigned pk2(float lo, float hi) { return f2bf(lo) | (f2bf(hi) << 16); }
; __device__ __forceinline__ void tr_item(const float* W, int ldw, int c0, bf16* WT, int ldk, int r0, int nblk, int item, LAS float* scr, int lane) {
;     ...
;     asm volatile("s_waitcnt lgkmcnt(0)" ::: "memory");
;     const int c = lane & 7;
; #pragma unroll
;     for (int j = 0; j < 4; ++j) { const int n = (lane >> 3) + 8 * j; const LAS float* s = scr + (8 * c) * 33 + n;
;         v4u o; o.x = pk2(s[0 * 33], s[1 * 33]); o.y = pk2(s[2 * 33], s[3 * 33]); o.z = pk2(s[4 * 33], s[5 * 33]); o.w = pk2(s[6 * 33], s[7 * 33]);
;         *(v4u*)(WT + (size_t)(r0 + n0 + n) * ldk + k0 + 8 * c) = o; }
;     asm volatile("s_waitcnt lgkmcnt(0)" ::: "memory");
; __device__ __forceinline__ void phase_convert_weights(const Ctx& C0, const Params& p, int l) {
;     ...
;     for (int it = gw; it < NITEMS; it += NGW) {
	s_waitcnt lgkmcnt(0)
	ds_read2_b32 v[36:37], v40 offset1:8
	ds_read2_b32 v[50:51], v40 offset0:33 offset1:41
	ds_read2_b32 v[52:53], v40 offset0:66 offset1:74
	ds_read2_b32 v[54:55], v40 offset0:99 offset1:107
	ds_read2_b32 v[56:57], v40 offset0:132 offset1:140
	ds_read2_b32 v[58:59], v40 offset0:165 offset1:173
	s_waitcnt lgkmcnt(5)
	v_bfe_u32 v0, v36, 16, 1
	v_add3_u32 v0, v36, v0, s80
	s_waitcnt lgkmcnt(4)
	v_bfe_u32 v7, v50, 16, 1
	v_lshrrev_b32_e32 v0, 16, v0
	v_add3_u32 v7, v50, v7, s80
	v_and_or_b32 v44, v7, s85, v0
	s_waitcnt lgkmcnt(3)
	v_bfe_u32 v0, v52, 16, 1
	v_add3_u32 v0, v52, v0, s80
	s_waitcnt lgkmcnt(2)
	v_bfe_u32 v7, v54, 16, 1
	ds_read2_b32 v[60:61], v40 offset0:198 offset1:206
	v_lshrrev_b32_e32 v0, 16, v0
	v_add3_u32 v7, v54, v7, s80
	ds_read2_b32 v[62:63], v40 offset0:231 offset1:239
	v_and_or_b32 v45, v7, s85, v0
	s_waitcnt lgkmcnt(3)
	v_bfe_u32 v0, v56, 16, 1
	v_add3_u32 v0, v56, v0, s80
	s_waitcnt lgkmcnt(2)
	v_bfe_u32 v7, v58, 16, 1
	v_lshrrev_b32_e32 v0, 16, v0
	v_add3_u32 v7, v58, v7, s80
	v_and_or_b32 v46, v7, s85, v0
	s_waitcnt lgkmcnt(1)
	v_bfe_u32 v0, v60, 16, 1
	v_add3_u32 v0, v60, v0, s80
	s_waitcnt lgkmcnt(0)
	v_bfe_u32 v7, v62, 16, 1
	v_lshrrev_b32_e32 v0, 16, v0
	v_add3_u32 v7, v62, v7, s80
	v_or_b32_e32 v64, s20, v39
	s_ashr_i32 s37, s36, 31
	v_and_or_b32 v47, v7, s85, v0
	v_ashrrev_i32_e32 v65, 31, v64
	v_bfe_u32 v0, v37, 16, 1
	v_lshl_add_u64 v[48:49], s[36:37], 1, v[30:31]
	v_lshlrev_b64 v[64:65], 11, v[64:65]
	v_add3_u32 v0, v37, v0, s80
	v_bfe_u32 v7, v51, 16, 1
	v_lshl_add_u64 v[64:65], v[48:49], 0, v[64:65]
	v_lshrrev_b32_e32 v0, 16, v0
	v_add3_u32 v7, v51, v7, s80
	global_store_dwordx4 v[64:65], v[44:47], off
	v_or_b32_e32 v36, s20, v41
	v_ashrrev_i32_e32 v37, 31, v36
	v_and_or_b32 v44, v7, s85, v0
	v_bfe_u32 v0, v53, 16, 1
	v_add3_u32 v0, v53, v0, s80
	v_bfe_u32 v7, v55, 16, 1
	v_lshrrev_b32_e32 v0, 16, v0
	v_add3_u32 v7, v55, v7, s80
	v_and_or_b32 v45, v7, s85, v0
	v_bfe_u32 v0, v57, 16, 1
	v_add3_u32 v0, v57, v0, s80
	v_bfe_u32 v7, v59, 16, 1
	v_lshrrev_b32_e32 v0, 16, v0
	v_add3_u32 v7, v59, v7, s80
	v_and_or_b32 v46, v7, s85, v0
	v_bfe_u32 v0, v61, 16, 1
	v_add3_u32 v0, v61, v0, s80
	v_bfe_u32 v7, v63, 16, 1
	v_lshrrev_b32_e32 v0, 16, v0
	v_add3_u32 v7, v63, v7, s80
	v_lshlrev_b64 v[36:37], 11, v[36:37]
	v_and_or_b32 v47, v7, s85, v0
	ds_read2_b32 v[50:51], v40 offset0:16 offset1:24
	v_lshl_add_u64 v[36:37], v[48:49], 0, v[36:37]
	global_store_dwordx4 v[36:37], v[44:47], off
	ds_read2_b32 v[36:37], v40 offset0:49 offset1:57
	ds_read2_b32 v[52:53], v40 offset0:82 offset1:90
	ds_read2_b32 v[54:55], v40 offset0:115 offset1:123
	s_waitcnt lgkmcnt(3)
	v_bfe_u32 v0, v50, 16, 1
	v_add3_u32 v0, v50, v0, s80
	s_waitcnt lgkmcnt(2)
	v_bfe_u32 v7, v36, 16, 1
	ds_read2_b32 v[56:57], v40 offset0:148 offset1:156
	v_lshrrev_b32_e32 v0, 16, v0
	v_add3_u32 v7, v36, v7, s80
	ds_read2_b32 v[58:59], v40 offset0:181 offset1:189
	v_and_or_b32 v44, v7, s85, v0
	s_waitcnt lgkmcnt(3)
	v_bfe_u32 v0, v52, 16, 1
	v_add3_u32 v0, v52, v0, s80
	s_waitcnt lgkmcnt(2)
	v_bfe_u32 v7, v54, 16, 1
	ds_read2_b32 v[60:61], v40 offset0:214 offset1:222
	v_lshrrev_b32_e32 v0, 16, v0
	v_add3_u32 v7, v54, v7, s80
	ds_read2_b32 v[62:63], v40 offset0:247 offset1:255
	v_and_or_b32 v45, v7, s85, v0
	s_waitcnt lgkmcnt(3)
	v_bfe_u32 v0, v56, 16, 1
	v_add3_u32 v0, v56, v0, s80
	s_waitcnt lgkmcnt(2)
	v_bfe_u32 v7, v58, 16, 1
	v_lshrrev_b32_e32 v0, 16, v0
	v_add3_u32 v7, v58, v7, s80
	v_and_or_b32 v46, v7, s85, v0
	s_waitcnt lgkmcnt(1)
	v_bfe_u32 v0, v60, 16, 1
	v_add3_u32 v0, v60, v0, s80
	s_waitcnt lgkmcnt(0)
	v_bfe_u32 v7, v62, 16, 1
	v_lshrrev_b32_e32 v0, 16, v0
	v_add3_u32 v7, v62, v7, s80
	v_or_b32_e32 v64, s20, v42
	v_and_or_b32 v47, v7, s85, v0
	v_ashrrev_i32_e32 v65, 31, v64
	v_bfe_u32 v0, v51, 16, 1
	v_lshlrev_b64 v[64:65], 11, v[64:65]
	v_add3_u32 v0, v51, v0, s80
	v_bfe_u32 v7, v37, 16, 1
	v_lshl_add_u64 v[64:65], v[48:49], 0, v[64:65]
	v_lshrrev_b32_e32 v0, 16, v0
	v_add3_u32 v7, v37, v7, s80
	global_store_dwordx4 v[64:65], v[44:47], off
	v_or_b32_e32 v36, s20, v43
	v_ashrrev_i32_e32 v37, 31, v36
	v_and_or_b32 v44, v7, s85, v0
	v_bfe_u32 v0, v53, 16, 1
	v_add3_u32 v0, v53, v0, s80
	v_bfe_u32 v7, v55, 16, 1
	v_lshrrev_b32_e32 v0, 16, v0
	v_add3_u32 v7, v55, v7, s80
	v_and_or_b32 v45, v7, s85, v0
	v_bfe_u32 v0, v57, 16, 1
	v_add3_u32 v0, v57, v0, s80
	v_bfe_u32 v7, v59, 16, 1
	v_lshrrev_b32_e32 v0, 16, v0
	v_add3_u32 v7, v59, v7, s80
	v_and_or_b32 v46, v7, s85, v0
	v_bfe_u32 v0, v61, 16, 1
	v_add3_u32 v0, v61, v0, s80
	v_bfe_u32 v7, v63, 16, 1
	v_lshrrev_b32_e32 v0, 16, v0
	v_add3_u32 v7, v63, v7, s80
	v_lshlrev_b64 v[36:37], 11, v[36:37]
	v_and_or_b32 v47, v7, s85, v0
	v_lshl_add_u64 v[36:37], v[48:49], 0, v[36:37]
	global_store_dwordx4 v[36:37], v[44:47], off
	s_waitcnt lgkmcnt(0)
	s_branch .LBB0_28
